# tail: non-temporal (nt) policy on single-use streams (hpost inputs, x residual loads, hb/pp epilogue loads, final-norm loads and output stores)
# speedup vs baseline: 1.0051x; 1.0051x over previous
.LBB0_524:
	s_nop 0
	v_lshl_add_u64 v[10:11], s[6:7], 0, v[184:185]
	v_add_co_u32_e64 v24, s[0:1], s14, v10
	v_lshl_add_u64 v[12:13], s[12:13], 0, v[184:185]
	s_nop 0
	v_addc_co_u32_e64 v25, s[0:1], 0, v11, s[0:1]
	v_add_co_u32_e32 v26, vcc, 0x2c000000, v12
	v_add_co_u32_e64 v16, s[0:1], s15, v12
	s_nop 0
	v_addc_co_u32_e32 v27, vcc, 0, v13, vcc
	v_addc_co_u32_e64 v17, s[0:1], 0, v13, s[0:1]
	v_add_co_u32_e64 v18, s[0:1], s16, v12
	v_add_co_u32_e32 v28, vcc, 0x30000000, v12
	s_nop 0
	v_addc_co_u32_e64 v19, s[0:1], 0, v13, s[0:1]
	v_addc_co_u32_e32 v29, vcc, 0, v13, vcc
	v_add_co_u32_e64 v20, s[0:1], s17, v12
	v_add_co_u32_e32 v12, vcc, 0x28000000, v12
	s_nop 0
	v_addc_co_u32_e64 v21, s[0:1], 0, v13, s[0:1]
	global_load_dwordx4 v[36:39], v[26:27], off nt
	global_load_dwordx4 v[40:43], v[28:29], off nt
	v_addc_co_u32_e32 v13, vcc, 0, v13, vcc
	global_load_dwordx4 v[44:47], v[12:13], off nt
	v_add_co_u32_e64 v22, s[0:1], s18, v10
	s_add_u32 s6, s6, 0x4000
	s_nop 0
	v_addc_co_u32_e64 v23, s[0:1], 0, v11, s[0:1]
	v_add_co_u32_e64 v14, s[0:1], s19, v10
	s_addc_u32 s7, s7, 0
	s_nop 0
	v_addc_co_u32_e64 v15, s[0:1], 0, v11, s[0:1]
	s_add_u32 s12, s12, 0x2000
	s_addc_u32 s13, s13, 0
	s_add_i32 s2, s2, -8
	s_cmp_eq_u32 s2, 0
	s_waitcnt vmcnt(0)
	v_lshlrev_b32_e32 v48, 16, v39
	v_and_b32_e32 v49, 0xffff0000, v39
	v_lshlrev_b32_e32 v50, 16, v38
	v_and_b32_e32 v51, 0xffff0000, v38
	v_lshlrev_b32_e32 v38, 16, v37
	v_and_b32_e32 v39, 0xffff0000, v37
	v_lshlrev_b32_e32 v52, 16, v36
	v_and_b32_e32 v53, 0xffff0000, v36
	v_lshlrev_b32_e32 v36, 16, v43
	v_and_b32_e32 v37, 0xffff0000, v43
	v_lshlrev_b32_e32 v54, 16, v42
	v_and_b32_e32 v55, 0xffff0000, v42
	v_lshlrev_b32_e32 v42, 16, v41
	v_and_b32_e32 v43, 0xffff0000, v41
	v_lshlrev_b32_e32 v56, 16, v40
	v_and_b32_e32 v57, 0xffff0000, v40
	v_pk_add_f32 v[36:37], v[48:49], v[36:37]
	v_lshlrev_b32_e32 v40, 16, v47
	v_and_b32_e32 v41, 0xffff0000, v47
	v_pk_add_f32 v[48:49], v[50:51], v[54:55]
	v_lshlrev_b32_e32 v50, 16, v46
	v_and_b32_e32 v51, 0xffff0000, v46
	v_pk_add_f32 v[38:39], v[38:39], v[42:43]
	v_and_b32_e32 v43, 0xffff0000, v45
	v_pk_add_f32 v[46:47], v[52:53], v[56:57]
	v_lshlrev_b32_e32 v42, 16, v45
	v_and_b32_e32 v53, 0xffff0000, v44
	v_mul_f32_e32 v60, 0xbfb8aa3b, v50
	v_mul_f32_e32 v63, 0xbfb8aa3b, v43
	v_pk_mul_f32 v[58:59], v[46:47], v[46:47]
	v_lshlrev_b32_e32 v52, 16, v44
	v_pk_mul_f32 v[56:57], v[38:39], v[38:39]
	v_mul_f32_e32 v62, 0xbfb8aa3b, v42
	v_mul_f32_e32 v65, 0xbfb8aa3b, v53
	v_exp_f32_e32 v60, v60
	v_exp_f32_e32 v63, v63
	v_add_f32_e32 v58, v58, v59
	v_mul_f32_e32 v61, 0xbfb8aa3b, v51
	v_mul_f32_e32 v64, 0xbfb8aa3b, v52
	v_mul_f32_e32 v66, 0xbfb8aa3b, v40
	v_exp_f32_e32 v62, v62
	v_exp_f32_e32 v65, v65
	v_add_f32_e32 v56, v56, v58
	v_pk_mul_f32 v[54:55], v[48:49], v[48:49]
	v_exp_f32_e32 v61, v61
	v_exp_f32_e32 v64, v64
	v_exp_f32_e32 v59, v66
	v_add_f32_e32 v56, v57, v56
	v_add_f32_e32 v54, v54, v56
	v_pk_mul_f32 v[44:45], v[36:37], v[36:37]
	v_add_f32_e32 v56, 1.0, v60
	v_add_f32_e32 v60, 1.0, v63
	v_add_f32_e32 v63, v55, v54
	v_add_f32_e32 v58, 1.0, v62
	v_add_f32_e32 v62, 1.0, v65
	v_add_f32_e32 v44, v44, v63
	v_add_f32_e32 v57, 1.0, v61
	v_add_f32_e32 v61, 1.0, v64
	v_add_f32_e32 v64, 1.0, v59
	v_rcp_f32_e32 v59, v62
	v_add_f32_e32 v62, v45, v44
	ds_bpermute_b32 v63, v31, v62
	v_rcp_f32_e32 v54, v56
	v_rcp_f32_e32 v55, v57
	v_rcp_f32_e32 v56, v58
	v_rcp_f32_e32 v58, v61
	v_mul_f32_e32 v67, 0xbfb8aa3b, v41
	v_pk_mul_f32 v[44:45], v[54:55], v[50:51]
	v_exp_f32_e32 v66, v67
	v_pk_mul_f32 v[50:51], v[58:59], v[52:53]
	s_waitcnt lgkmcnt(0)
	v_add_f32_e32 v52, v62, v63
	ds_bpermute_b32 v53, v32, v52
	v_add_f32_e32 v65, 1.0, v66
	v_rcp_f32_e32 v57, v60
	v_rcp_f32_e32 v60, v64
	v_rcp_f32_e32 v61, v65
	s_waitcnt lgkmcnt(0)
	v_add_f32_e32 v52, v52, v53
	ds_bpermute_b32 v53, v33, v52
	v_pk_mul_f32 v[42:43], v[56:57], v[42:43]
	v_pk_mul_f32 v[40:41], v[60:61], v[40:41]
	s_waitcnt lgkmcnt(0)
	v_add_f32_e32 v52, v52, v53
	ds_bpermute_b32 v53, v34, v52
	s_waitcnt lgkmcnt(0)
	v_add_f32_e32 v52, v52, v53
	v_fmamk_f32 v52, v52, 0x3c000000, v35
	v_mul_f32_e32 v53, 0x4b800000, v52
	v_cmp_gt_f32_e32 vcc, s3, v52
	s_nop 1
	v_cndmask_b32_e32 v52, v52, v53, vcc
	v_rsq_f32_e32 v52, v52
	s_nop 0
	v_mul_f32_e32 v53, 0x45800000, v52
	v_cndmask_b32_e32 v52, v52, v53, vcc
	v_pk_mul_f32 v[46:47], v[46:47], v[52:53] op_sel_hi:[1,0]
	v_pk_mul_f32 v[38:39], v[38:39], v[52:53] op_sel_hi:[1,0]
	v_pk_mul_f32 v[48:49], v[48:49], v[52:53] op_sel_hi:[1,0]
	v_pk_mul_f32 v[36:37], v[36:37], v[52:53] op_sel_hi:[1,0]
	v_pk_mul_f32 v[46:47], v[2:3], v[46:47]
	v_pk_mul_f32 v[38:39], v[4:5], v[38:39]
	v_pk_mul_f32 v[48:49], v[6:7], v[48:49]
	v_pk_mul_f32 v[36:37], v[8:9], v[36:37]
	v_pk_mul_f32 v[46:47], v[50:51], v[46:47]
	v_pk_mul_f32 v[38:39], v[42:43], v[38:39]
	v_pk_mul_f32 v[42:43], v[44:45], v[48:49]
	v_pk_mul_f32 v[40:41], v[40:41], v[36:37]
	v_cvt_pk_bf16_f32 v36, v46, v47
	v_cvt_pk_bf16_f32 v37, v38, v39
	v_cvt_pk_bf16_f32 v38, v42, v43
	v_cvt_pk_bf16_f32 v39, v40, v41
	global_store_dwordx4 v[10:11], v[36:39], off offset:1024
	global_load_dwordx4 v[36:39], v[26:27], off offset:1024 nt
	s_nop 0
	global_load_dwordx4 v[40:43], v[28:29], off offset:1024 nt
	global_load_dwordx4 v[44:47], v[12:13], off offset:1024 nt
	s_waitcnt vmcnt(2)
	v_lshlrev_b32_e32 v48, 16, v39
	v_and_b32_e32 v49, 0xffff0000, v39
	s_waitcnt vmcnt(1)
	v_lshlrev_b32_e32 v50, 16, v43
	v_and_b32_e32 v51, 0xffff0000, v43
	s_waitcnt vmcnt(0)
	v_lshlrev_b32_e32 v52, 16, v47
	v_and_b32_e32 v53, 0xffff0000, v47
	v_lshlrev_b32_e32 v54, 16, v38
	v_and_b32_e32 v55, 0xffff0000, v38
	v_lshlrev_b32_e32 v38, 16, v42
	v_and_b32_e32 v39, 0xffff0000, v42
	v_lshlrev_b32_e32 v42, 16, v46
	v_and_b32_e32 v43, 0xffff0000, v46
	v_lshlrev_b32_e32 v46, 16, v37
	v_and_b32_e32 v47, 0xffff0000, v37
	v_lshlrev_b32_e32 v56, 16, v41
	v_and_b32_e32 v57, 0xffff0000, v41
	v_lshlrev_b32_e32 v58, 16, v45
	v_and_b32_e32 v59, 0xffff0000, v45
	v_lshlrev_b32_e32 v60, 16, v36
	v_and_b32_e32 v61, 0xffff0000, v36
	v_lshlrev_b32_e32 v36, 16, v40
	v_and_b32_e32 v37, 0xffff0000, v40
	v_pk_add_f32 v[38:39], v[54:55], v[38:39]
	v_mul_f32_e32 v54, 0xbfb8aa3b, v42
	v_mul_f32_e32 v55, 0xbfb8aa3b, v43
	v_pk_add_f32 v[46:47], v[46:47], v[56:57]
	v_mul_f32_e32 v56, 0xbfb8aa3b, v58
	v_mul_f32_e32 v57, 0xbfb8aa3b, v59
	v_pk_add_f32 v[36:37], v[60:61], v[36:37]
	v_exp_f32_e32 v64, v54
	v_exp_f32_e32 v65, v55
	v_exp_f32_e32 v66, v56
	v_exp_f32_e32 v67, v57
	v_pk_mul_f32 v[56:57], v[36:37], v[36:37]
	v_mul_f32_e32 v62, 0xbfb8aa3b, v52
	v_pk_mul_f32 v[54:55], v[46:47], v[46:47]
	v_add_f32_e32 v56, v56, v57
	v_mul_f32_e32 v63, 0xbfb8aa3b, v53
	v_exp_f32_e32 v62, v62
	v_add_f32_e32 v54, v54, v56
	v_lshlrev_b32_e32 v40, 16, v44
	v_and_b32_e32 v41, 0xffff0000, v44
	v_pk_add_f32 v[44:45], v[48:49], v[50:51]
	v_pk_mul_f32 v[50:51], v[38:39], v[38:39]
	v_exp_f32_e32 v63, v63
	v_add_f32_e32 v54, v55, v54
	v_add_f32_e32 v55, 1.0, v64
	v_add_f32_e32 v56, 1.0, v65
	v_add_f32_e32 v57, 1.0, v66
	v_add_f32_e32 v64, 1.0, v67
	v_add_f32_e32 v50, v50, v54
	v_pk_mul_f32 v[48:49], v[44:45], v[44:45]
	v_rcp_f32_e32 v54, v55
	v_rcp_f32_e32 v55, v56
	v_rcp_f32_e32 v56, v57
	v_rcp_f32_e32 v57, v64
	v_add_f32_e32 v64, v51, v50
	v_add_f32_e32 v62, 1.0, v62
	v_add_f32_e32 v48, v48, v64
	v_add_f32_e32 v63, 1.0, v63
	v_rcp_f32_e32 v50, v62
	v_add_f32_e32 v62, v49, v48
	v_rcp_f32_e32 v51, v63
	ds_bpermute_b32 v63, v31, v62
	v_mul_f32_e32 v60, 0xbfb8aa3b, v40
	v_mul_f32_e32 v61, 0xbfb8aa3b, v41
	v_pk_mul_f32 v[50:51], v[50:51], v[52:53]
	v_exp_f32_e32 v60, v60
	s_waitcnt lgkmcnt(0)
	v_add_f32_e32 v52, v62, v63
	ds_bpermute_b32 v53, v32, v52
	v_exp_f32_e32 v61, v61
	v_add_f32_e32 v60, 1.0, v60
	v_rcp_f32_e32 v60, v60
	v_pk_mul_f32 v[42:43], v[54:55], v[42:43]
	s_waitcnt lgkmcnt(0)
	v_add_f32_e32 v52, v52, v53
	ds_bpermute_b32 v53, v33, v52
	v_add_f32_e32 v61, 1.0, v61
	v_rcp_f32_e32 v61, v61
	v_pk_mul_f32 v[48:49], v[56:57], v[58:59]
	s_waitcnt lgkmcnt(0)
	v_add_f32_e32 v52, v52, v53
	ds_bpermute_b32 v53, v34, v52
	v_pk_mul_f32 v[40:41], v[60:61], v[40:41]
	s_waitcnt lgkmcnt(0)
	v_add_f32_e32 v52, v52, v53
	v_fmamk_f32 v52, v52, 0x3c000000, v35
	v_mul_f32_e32 v53, 0x4b800000, v52
	v_cmp_gt_f32_e32 vcc, s3, v52
	s_nop 1
	v_cndmask_b32_e32 v52, v52, v53, vcc
	v_rsq_f32_e32 v52, v52
	s_nop 0
	v_mul_f32_e32 v53, 0x45800000, v52
	v_cndmask_b32_e32 v52, v52, v53, vcc
	v_pk_mul_f32 v[36:37], v[36:37], v[52:53] op_sel_hi:[1,0]
	v_pk_mul_f32 v[46:47], v[46:47], v[52:53] op_sel_hi:[1,0]
	v_pk_mul_f32 v[38:39], v[38:39], v[52:53] op_sel_hi:[1,0]
	v_pk_mul_f32 v[44:45], v[44:45], v[52:53] op_sel_hi:[1,0]
	v_pk_mul_f32 v[36:37], v[2:3], v[36:37]
	v_pk_mul_f32 v[46:47], v[4:5], v[46:47]
	v_pk_mul_f32 v[38:39], v[6:7], v[38:39]
	v_pk_mul_f32 v[44:45], v[8:9], v[44:45]
	v_pk_mul_f32 v[36:37], v[40:41], v[36:37]
	v_pk_mul_f32 v[40:41], v[48:49], v[46:47]
	v_pk_mul_f32 v[38:39], v[42:43], v[38:39]
	v_pk_mul_f32 v[42:43], v[50:51], v[44:45]
	v_cvt_pk_bf16_f32 v36, v36, v37
	v_cvt_pk_bf16_f32 v37, v40, v41
	v_cvt_pk_bf16_f32 v38, v38, v39
	v_cvt_pk_bf16_f32 v39, v42, v43
	global_store_dwordx4 v[10:11], v[36:39], off offset:3072
	global_load_dwordx4 v[36:39], v[26:27], off offset:2048 nt
	s_nop 0
	global_load_dwordx4 v[40:43], v[28:29], off offset:2048 nt
	global_load_dwordx4 v[44:47], v[12:13], off offset:2048 nt
	s_waitcnt vmcnt(2)
	v_lshlrev_b32_e32 v10, 16, v39
	v_and_b32_e32 v11, 0xffff0000, v39
	s_waitcnt vmcnt(1)
	v_lshlrev_b32_e32 v48, 16, v43
	v_and_b32_e32 v49, 0xffff0000, v43
	s_waitcnt vmcnt(0)
	v_lshlrev_b32_e32 v50, 16, v47
	v_and_b32_e32 v51, 0xffff0000, v47
	v_lshlrev_b32_e32 v52, 16, v38
	v_and_b32_e32 v53, 0xffff0000, v38
	v_lshlrev_b32_e32 v38, 16, v42
	v_and_b32_e32 v39, 0xffff0000, v42
	v_lshlrev_b32_e32 v42, 16, v46
	v_and_b32_e32 v43, 0xffff0000, v46
	v_lshlrev_b32_e32 v46, 16, v37
	v_and_b32_e32 v47, 0xffff0000, v37
	v_lshlrev_b32_e32 v54, 16, v41
	v_and_b32_e32 v55, 0xffff0000, v41
	v_lshlrev_b32_e32 v56, 16, v45
	v_and_b32_e32 v57, 0xffff0000, v45
	v_lshlrev_b32_e32 v58, 16, v36
	v_and_b32_e32 v59, 0xffff0000, v36
	v_lshlrev_b32_e32 v36, 16, v40
	v_and_b32_e32 v37, 0xffff0000, v40
	v_lshlrev_b32_e32 v40, 16, v44
	v_and_b32_e32 v41, 0xffff0000, v44
	v_pk_add_f32 v[38:39], v[52:53], v[38:39]
	v_mul_f32_e32 v52, 0xbfb8aa3b, v42
	v_mul_f32_e32 v53, 0xbfb8aa3b, v43
	v_pk_add_f32 v[44:45], v[46:47], v[54:55]
	v_mul_f32_e32 v54, 0xbfb8aa3b, v56
	v_mul_f32_e32 v55, 0xbfb8aa3b, v57
	v_pk_add_f32 v[36:37], v[58:59], v[36:37]
	v_exp_f32_e32 v62, v52
	v_exp_f32_e32 v63, v53
	v_exp_f32_e32 v64, v54
	v_exp_f32_e32 v65, v55
	v_pk_mul_f32 v[54:55], v[36:37], v[36:37]
	v_mul_f32_e32 v60, 0xbfb8aa3b, v50
	v_pk_mul_f32 v[52:53], v[44:45], v[44:45]
	v_add_f32_e32 v54, v54, v55
	v_mul_f32_e32 v61, 0xbfb8aa3b, v51
	v_exp_f32_e32 v60, v60
	v_add_f32_e32 v52, v52, v54
	v_pk_add_f32 v[10:11], v[10:11], v[48:49]
	v_pk_mul_f32 v[48:49], v[38:39], v[38:39]
	v_exp_f32_e32 v61, v61
	v_add_f32_e32 v52, v53, v52
	v_add_f32_e32 v53, 1.0, v62
	v_add_f32_e32 v54, 1.0, v63
	v_add_f32_e32 v55, 1.0, v64
	v_add_f32_e32 v62, 1.0, v65
	v_add_f32_e32 v48, v48, v52
	v_pk_mul_f32 v[46:47], v[10:11], v[10:11]
	v_rcp_f32_e32 v52, v53
	v_rcp_f32_e32 v53, v54
	v_rcp_f32_e32 v54, v55
	v_rcp_f32_e32 v55, v62
	v_add_f32_e32 v62, v49, v48
	v_add_f32_e32 v60, 1.0, v60
	v_add_f32_e32 v46, v46, v62
	v_add_f32_e32 v61, 1.0, v61
	v_rcp_f32_e32 v48, v60
	v_add_f32_e32 v60, v47, v46
	v_rcp_f32_e32 v49, v61
	ds_bpermute_b32 v61, v31, v60
	v_mul_f32_e32 v58, 0xbfb8aa3b, v40
	v_mul_f32_e32 v59, 0xbfb8aa3b, v41
	v_pk_mul_f32 v[48:49], v[48:49], v[50:51]
	v_exp_f32_e32 v58, v58
	s_waitcnt lgkmcnt(0)
	v_add_f32_e32 v50, v60, v61
	ds_bpermute_b32 v51, v32, v50
	v_exp_f32_e32 v59, v59
	v_add_f32_e32 v58, 1.0, v58
	v_rcp_f32_e32 v58, v58
	v_pk_mul_f32 v[42:43], v[52:53], v[42:43]
	s_waitcnt lgkmcnt(0)
	v_add_f32_e32 v50, v50, v51
	ds_bpermute_b32 v51, v33, v50
	v_add_f32_e32 v59, 1.0, v59
	v_rcp_f32_e32 v59, v59
	v_pk_mul_f32 v[46:47], v[54:55], v[56:57]
	s_waitcnt lgkmcnt(0)
	v_add_f32_e32 v50, v50, v51
	ds_bpermute_b32 v51, v34, v50
	v_pk_mul_f32 v[40:41], v[58:59], v[40:41]
	s_waitcnt lgkmcnt(0)
	v_add_f32_e32 v50, v50, v51
	v_fmamk_f32 v50, v50, 0x3c000000, v35
	v_mul_f32_e32 v51, 0x4b800000, v50
	v_cmp_gt_f32_e32 vcc, s3, v50
	s_nop 1
	v_cndmask_b32_e32 v50, v50, v51, vcc
	v_rsq_f32_e32 v50, v50
	s_nop 0
	v_mul_f32_e32 v51, 0x45800000, v50
	v_cndmask_b32_e32 v50, v50, v51, vcc
	v_pk_mul_f32 v[36:37], v[36:37], v[50:51] op_sel_hi:[1,0]
	v_pk_mul_f32 v[44:45], v[44:45], v[50:51] op_sel_hi:[1,0]
	v_pk_mul_f32 v[38:39], v[38:39], v[50:51] op_sel_hi:[1,0]
	v_pk_mul_f32 v[10:11], v[10:11], v[50:51] op_sel_hi:[1,0]
	v_pk_mul_f32 v[36:37], v[2:3], v[36:37]
	v_pk_mul_f32 v[44:45], v[4:5], v[44:45]
	v_pk_mul_f32 v[38:39], v[6:7], v[38:39]
	v_pk_mul_f32 v[10:11], v[8:9], v[10:11]
	v_pk_mul_f32 v[36:37], v[40:41], v[36:37]
	v_pk_mul_f32 v[40:41], v[46:47], v[44:45]
	v_pk_mul_f32 v[38:39], v[42:43], v[38:39]
	v_pk_mul_f32 v[10:11], v[48:49], v[10:11]
	v_cvt_pk_bf16_f32 v36, v36, v37
	v_cvt_pk_bf16_f32 v37, v40, v41
	v_cvt_pk_bf16_f32 v38, v38, v39
	v_cvt_pk_bf16_f32 v39, v10, v11
	global_store_dwordx4 v[24:25], v[36:39], off offset:1024
	global_load_dwordx4 v[36:39], v[26:27], off offset:3072 nt
	s_nop 0
	global_load_dwordx4 v[40:43], v[28:29], off offset:3072 nt
	global_load_dwordx4 v[44:47], v[12:13], off offset:3072 nt
	s_waitcnt vmcnt(2)
	v_lshlrev_b32_e32 v10, 16, v39
	v_and_b32_e32 v11, 0xffff0000, v39
	s_waitcnt vmcnt(1)
	v_lshlrev_b32_e32 v12, 16, v43
	v_and_b32_e32 v13, 0xffff0000, v43
	s_waitcnt vmcnt(0)
	v_lshlrev_b32_e32 v26, 16, v47
	v_and_b32_e32 v27, 0xffff0000, v47
	v_lshlrev_b32_e32 v28, 16, v38
	v_and_b32_e32 v29, 0xffff0000, v38
	v_lshlrev_b32_e32 v38, 16, v42
	v_and_b32_e32 v39, 0xffff0000, v42
	v_lshlrev_b32_e32 v42, 16, v46
	v_and_b32_e32 v43, 0xffff0000, v46
	v_lshlrev_b32_e32 v46, 16, v37
	v_and_b32_e32 v47, 0xffff0000, v37
	v_lshlrev_b32_e32 v48, 16, v41
	v_and_b32_e32 v49, 0xffff0000, v41
	v_lshlrev_b32_e32 v50, 16, v45
	v_and_b32_e32 v51, 0xffff0000, v45
	v_lshlrev_b32_e32 v52, 16, v36
	v_and_b32_e32 v53, 0xffff0000, v36
	v_lshlrev_b32_e32 v36, 16, v40
	v_and_b32_e32 v37, 0xffff0000, v40
	v_pk_add_f32 v[10:11], v[10:11], v[12:13]
	v_pk_add_f32 v[12:13], v[28:29], v[38:39]
	v_mul_f32_e32 v54, 0xbfb8aa3b, v42
	v_mul_f32_e32 v55, 0xbfb8aa3b, v43
	v_pk_add_f32 v[28:29], v[46:47], v[48:49]
	v_mul_f32_e32 v48, 0xbfb8aa3b, v50
	v_mul_f32_e32 v49, 0xbfb8aa3b, v51
	v_pk_add_f32 v[36:37], v[52:53], v[36:37]
	v_exp_f32_e32 v54, v54
	v_exp_f32_e32 v55, v55
	v_exp_f32_e32 v58, v48
	v_exp_f32_e32 v59, v49
	v_pk_mul_f32 v[48:49], v[36:37], v[36:37]
	v_pk_mul_f32 v[46:47], v[28:29], v[28:29]
	v_add_f32_e32 v48, v48, v49
	v_mul_f32_e32 v56, 0xbfb8aa3b, v26
	v_add_f32_e32 v46, v46, v48
	v_lshlrev_b32_e32 v40, 16, v44
	v_and_b32_e32 v41, 0xffff0000, v44
	v_mul_f32_e32 v57, 0xbfb8aa3b, v27
	v_pk_mul_f32 v[44:45], v[12:13], v[12:13]
	v_exp_f32_e32 v56, v56
	v_add_f32_e32 v46, v47, v46
	v_exp_f32_e32 v57, v57
	v_add_f32_e32 v47, 1.0, v54
	v_add_f32_e32 v48, 1.0, v55
	v_add_f32_e32 v49, 1.0, v58
	v_add_f32_e32 v54, 1.0, v59
	v_add_f32_e32 v44, v44, v46
	v_pk_mul_f32 v[38:39], v[10:11], v[10:11]
	v_rcp_f32_e32 v46, v47
	v_rcp_f32_e32 v47, v48
	v_rcp_f32_e32 v48, v49
	v_rcp_f32_e32 v49, v54
	v_add_f32_e32 v54, v45, v44
	v_add_f32_e32 v38, v38, v54
	v_add_f32_e32 v55, 1.0, v56
	v_add_f32_e32 v54, v39, v38
	v_add_f32_e32 v56, 1.0, v57
	v_rcp_f32_e32 v44, v55
	ds_bpermute_b32 v55, v31, v54
	v_rcp_f32_e32 v45, v56
	v_mul_f32_e32 v52, 0xbfb8aa3b, v40
	v_mul_f32_e32 v53, 0xbfb8aa3b, v41
	v_exp_f32_e32 v52, v52
	v_pk_mul_f32 v[26:27], v[44:45], v[26:27]
	s_waitcnt lgkmcnt(0)
	v_add_f32_e32 v44, v54, v55
	ds_bpermute_b32 v45, v32, v44
	v_exp_f32_e32 v53, v53
	v_add_f32_e32 v52, 1.0, v52
	v_rcp_f32_e32 v52, v52
	v_pk_mul_f32 v[38:39], v[46:47], v[42:43]
	s_waitcnt lgkmcnt(0)
	v_add_f32_e32 v44, v44, v45
	ds_bpermute_b32 v45, v33, v44
	v_add_f32_e32 v53, 1.0, v53
	v_rcp_f32_e32 v53, v53
	v_pk_mul_f32 v[42:43], v[48:49], v[50:51]
	s_waitcnt lgkmcnt(0)
	v_add_f32_e32 v44, v44, v45
	ds_bpermute_b32 v45, v34, v44
	v_pk_mul_f32 v[40:41], v[52:53], v[40:41]
	s_waitcnt lgkmcnt(0)
	v_add_f32_e32 v44, v44, v45
	v_fmamk_f32 v44, v44, 0x3c000000, v35
	v_mul_f32_e32 v45, 0x4b800000, v44
	v_cmp_gt_f32_e32 vcc, s3, v44
	s_nop 1
	v_cndmask_b32_e32 v44, v44, v45, vcc
	v_rsq_f32_e32 v44, v44
	s_nop 0
	v_mul_f32_e32 v45, 0x45800000, v44
	v_cndmask_b32_e32 v44, v44, v45, vcc
	v_pk_mul_f32 v[36:37], v[36:37], v[44:45] op_sel_hi:[1,0]
	v_pk_mul_f32 v[28:29], v[28:29], v[44:45] op_sel_hi:[1,0]
	v_pk_mul_f32 v[12:13], v[12:13], v[44:45] op_sel_hi:[1,0]
	v_pk_mul_f32 v[10:11], v[10:11], v[44:45] op_sel_hi:[1,0]
	v_pk_mul_f32 v[36:37], v[2:3], v[36:37]
	v_pk_mul_f32 v[28:29], v[4:5], v[28:29]
	v_pk_mul_f32 v[12:13], v[6:7], v[12:13]
	v_pk_mul_f32 v[10:11], v[8:9], v[10:11]
	v_pk_mul_f32 v[36:37], v[40:41], v[36:37]
	v_pk_mul_f32 v[28:29], v[42:43], v[28:29]
	v_pk_mul_f32 v[12:13], v[38:39], v[12:13]
	v_pk_mul_f32 v[26:27], v[26:27], v[10:11]
	v_cvt_pk_bf16_f32 v10, v36, v37
	v_cvt_pk_bf16_f32 v11, v28, v29
	v_cvt_pk_bf16_f32 v12, v12, v13
	v_cvt_pk_bf16_f32 v13, v26, v27
	global_store_dwordx4 v[24:25], v[10:13], off offset:3072
	global_load_dwordx4 v[10:13], v[16:17], off nt
	s_nop 0
	global_load_dwordx4 v[24:27], v[18:19], off nt
	global_load_dwordx4 v[36:39], v[20:21], off nt
	s_waitcnt vmcnt(2)
	v_lshlrev_b32_e32 v28, 16, v13
	v_and_b32_e32 v29, 0xffff0000, v13
	s_waitcnt vmcnt(1)
	v_lshlrev_b32_e32 v40, 16, v27
	v_and_b32_e32 v41, 0xffff0000, v27
	s_waitcnt vmcnt(0)
	v_lshlrev_b32_e32 v42, 16, v39
	v_and_b32_e32 v43, 0xffff0000, v39
	v_lshlrev_b32_e32 v44, 16, v12
	v_and_b32_e32 v45, 0xffff0000, v12
	v_lshlrev_b32_e32 v12, 16, v26
	v_and_b32_e32 v13, 0xffff0000, v26
	v_lshlrev_b32_e32 v26, 16, v38
	v_and_b32_e32 v27, 0xffff0000, v38
	v_lshlrev_b32_e32 v38, 16, v11
	v_and_b32_e32 v39, 0xffff0000, v11
	v_lshlrev_b32_e32 v46, 16, v25
	v_and_b32_e32 v47, 0xffff0000, v25
	v_lshlrev_b32_e32 v48, 16, v37
	v_and_b32_e32 v49, 0xffff0000, v37
	v_lshlrev_b32_e32 v50, 16, v10
	v_and_b32_e32 v51, 0xffff0000, v10
	v_lshlrev_b32_e32 v10, 16, v24
	v_and_b32_e32 v11, 0xffff0000, v24
	v_lshlrev_b32_e32 v24, 16, v36
	v_and_b32_e32 v25, 0xffff0000, v36
	v_pk_add_f32 v[12:13], v[44:45], v[12:13]
	v_mul_f32_e32 v44, 0xbfb8aa3b, v26
	v_mul_f32_e32 v45, 0xbfb8aa3b, v27
	v_pk_add_f32 v[36:37], v[38:39], v[46:47]
	v_mul_f32_e32 v46, 0xbfb8aa3b, v48
	v_mul_f32_e32 v47, 0xbfb8aa3b, v49
	v_pk_add_f32 v[10:11], v[50:51], v[10:11]
	v_exp_f32_e32 v54, v44
	v_exp_f32_e32 v55, v45
	v_exp_f32_e32 v56, v46
	v_exp_f32_e32 v57, v47
	v_pk_mul_f32 v[46:47], v[10:11], v[10:11]
	v_mul_f32_e32 v52, 0xbfb8aa3b, v42
	v_pk_mul_f32 v[44:45], v[36:37], v[36:37]
	v_add_f32_e32 v46, v46, v47
	v_mul_f32_e32 v53, 0xbfb8aa3b, v43
	v_exp_f32_e32 v52, v52
	v_add_f32_e32 v44, v44, v46
	v_pk_add_f32 v[28:29], v[28:29], v[40:41]
	v_pk_mul_f32 v[40:41], v[12:13], v[12:13]
	v_exp_f32_e32 v53, v53
	v_add_f32_e32 v44, v45, v44
	v_add_f32_e32 v45, 1.0, v54
	v_add_f32_e32 v46, 1.0, v55
	v_add_f32_e32 v47, 1.0, v56
	v_add_f32_e32 v54, 1.0, v57
	v_add_f32_e32 v40, v40, v44
	v_pk_mul_f32 v[38:39], v[28:29], v[28:29]
	v_rcp_f32_e32 v44, v45
	v_rcp_f32_e32 v45, v46
	v_rcp_f32_e32 v46, v47
	v_rcp_f32_e32 v47, v54
	v_add_f32_e32 v54, v41, v40
	v_add_f32_e32 v52, 1.0, v52
	v_add_f32_e32 v38, v38, v54
	v_add_f32_e32 v53, 1.0, v53
	v_rcp_f32_e32 v40, v52
	v_add_f32_e32 v52, v39, v38
	v_rcp_f32_e32 v41, v53
	ds_bpermute_b32 v53, v31, v52
	v_mul_f32_e32 v50, 0xbfb8aa3b, v24
	v_mul_f32_e32 v51, 0xbfb8aa3b, v25
	v_pk_mul_f32 v[40:41], v[40:41], v[42:43]
	v_exp_f32_e32 v50, v50
	s_waitcnt lgkmcnt(0)
	v_add_f32_e32 v42, v52, v53
	ds_bpermute_b32 v43, v32, v42
	v_exp_f32_e32 v51, v51
	v_add_f32_e32 v50, 1.0, v50
	v_rcp_f32_e32 v50, v50
	v_pk_mul_f32 v[26:27], v[44:45], v[26:27]
	s_waitcnt lgkmcnt(0)
	v_add_f32_e32 v42, v42, v43
	ds_bpermute_b32 v43, v33, v42
	v_add_f32_e32 v51, 1.0, v51
	v_rcp_f32_e32 v51, v51
	v_pk_mul_f32 v[38:39], v[46:47], v[48:49]
	s_waitcnt lgkmcnt(0)
	v_add_f32_e32 v42, v42, v43
	ds_bpermute_b32 v43, v34, v42
	v_pk_mul_f32 v[24:25], v[50:51], v[24:25]
	s_waitcnt lgkmcnt(0)
	v_add_f32_e32 v42, v42, v43
	v_fmamk_f32 v42, v42, 0x3c000000, v35
	v_mul_f32_e32 v43, 0x4b800000, v42
	v_cmp_gt_f32_e32 vcc, s3, v42
	s_nop 1
	v_cndmask_b32_e32 v42, v42, v43, vcc
	v_rsq_f32_e32 v42, v42
	s_nop 0
	v_mul_f32_e32 v43, 0x45800000, v42
	v_cndmask_b32_e32 v42, v42, v43, vcc
	v_pk_mul_f32 v[10:11], v[10:11], v[42:43] op_sel_hi:[1,0]
	v_pk_mul_f32 v[36:37], v[36:37], v[42:43] op_sel_hi:[1,0]
	v_pk_mul_f32 v[12:13], v[12:13], v[42:43] op_sel_hi:[1,0]
	v_pk_mul_f32 v[28:29], v[28:29], v[42:43] op_sel_hi:[1,0]
	v_pk_mul_f32 v[10:11], v[2:3], v[10:11]
	v_pk_mul_f32 v[36:37], v[4:5], v[36:37]
	v_pk_mul_f32 v[12:13], v[6:7], v[12:13]
	v_pk_mul_f32 v[28:29], v[8:9], v[28:29]
	v_pk_mul_f32 v[10:11], v[24:25], v[10:11]
	v_pk_mul_f32 v[24:25], v[38:39], v[36:37]
	v_pk_mul_f32 v[12:13], v[26:27], v[12:13]
	v_pk_mul_f32 v[26:27], v[40:41], v[28:29]
	v_cvt_pk_bf16_f32 v10, v10, v11
	v_cvt_pk_bf16_f32 v11, v24, v25
	v_cvt_pk_bf16_f32 v12, v12, v13
	v_cvt_pk_bf16_f32 v13, v26, v27
	global_store_dwordx4 v[22:23], v[10:13], off offset:1024
	global_load_dwordx4 v[10:13], v[16:17], off offset:1024 nt
	s_nop 0
	global_load_dwordx4 v[24:27], v[18:19], off offset:1024 nt
	global_load_dwordx4 v[36:39], v[20:21], off offset:1024 nt
	s_waitcnt vmcnt(2)
	v_lshlrev_b32_e32 v28, 16, v13
	v_and_b32_e32 v29, 0xffff0000, v13
	s_waitcnt vmcnt(1)
	v_lshlrev_b32_e32 v40, 16, v27
	v_and_b32_e32 v41, 0xffff0000, v27
	s_waitcnt vmcnt(0)
	v_lshlrev_b32_e32 v42, 16, v39
	v_and_b32_e32 v43, 0xffff0000, v39
	v_lshlrev_b32_e32 v44, 16, v12
	v_and_b32_e32 v45, 0xffff0000, v12
	v_lshlrev_b32_e32 v12, 16, v26
	v_and_b32_e32 v13, 0xffff0000, v26
	v_lshlrev_b32_e32 v26, 16, v38
	v_and_b32_e32 v27, 0xffff0000, v38
	v_lshlrev_b32_e32 v38, 16, v11
	v_and_b32_e32 v39, 0xffff0000, v11
	v_lshlrev_b32_e32 v46, 16, v25
	v_and_b32_e32 v47, 0xffff0000, v25
	v_lshlrev_b32_e32 v48, 16, v37
	v_and_b32_e32 v49, 0xffff0000, v37
	v_lshlrev_b32_e32 v50, 16, v10
	v_and_b32_e32 v51, 0xffff0000, v10
	v_lshlrev_b32_e32 v10, 16, v24
	v_and_b32_e32 v11, 0xffff0000, v24
	v_lshlrev_b32_e32 v24, 16, v36
	v_and_b32_e32 v25, 0xffff0000, v36
	v_pk_add_f32 v[12:13], v[44:45], v[12:13]
	v_mul_f32_e32 v44, 0xbfb8aa3b, v26
	v_mul_f32_e32 v45, 0xbfb8aa3b, v27
	v_pk_add_f32 v[36:37], v[38:39], v[46:47]
	v_mul_f32_e32 v46, 0xbfb8aa3b, v48
	v_mul_f32_e32 v47, 0xbfb8aa3b, v49
	v_pk_add_f32 v[10:11], v[50:51], v[10:11]
	v_exp_f32_e32 v54, v44
	v_exp_f32_e32 v55, v45
	v_exp_f32_e32 v56, v46
	v_exp_f32_e32 v57, v47
	v_pk_mul_f32 v[46:47], v[10:11], v[10:11]
	v_mul_f32_e32 v52, 0xbfb8aa3b, v42
	v_pk_mul_f32 v[44:45], v[36:37], v[36:37]
	v_add_f32_e32 v46, v46, v47
	v_mul_f32_e32 v53, 0xbfb8aa3b, v43
	v_exp_f32_e32 v52, v52
	v_add_f32_e32 v44, v44, v46
	v_pk_add_f32 v[28:29], v[28:29], v[40:41]
	v_pk_mul_f32 v[40:41], v[12:13], v[12:13]
	v_exp_f32_e32 v53, v53
	v_add_f32_e32 v44, v45, v44
	v_add_f32_e32 v45, 1.0, v54
	v_add_f32_e32 v46, 1.0, v55
	v_add_f32_e32 v47, 1.0, v56
	v_add_f32_e32 v54, 1.0, v57
	v_add_f32_e32 v40, v40, v44
	v_pk_mul_f32 v[38:39], v[28:29], v[28:29]
	v_rcp_f32_e32 v44, v45
	v_rcp_f32_e32 v45, v46
	v_rcp_f32_e32 v46, v47
	v_rcp_f32_e32 v47, v54
	v_add_f32_e32 v54, v41, v40
	v_add_f32_e32 v52, 1.0, v52
	v_add_f32_e32 v38, v38, v54
	v_add_f32_e32 v53, 1.0, v53
	v_rcp_f32_e32 v40, v52
	v_add_f32_e32 v52, v39, v38
	v_rcp_f32_e32 v41, v53
	ds_bpermute_b32 v53, v31, v52
	v_mul_f32_e32 v50, 0xbfb8aa3b, v24
	v_mul_f32_e32 v51, 0xbfb8aa3b, v25
	v_pk_mul_f32 v[40:41], v[40:41], v[42:43]
	v_exp_f32_e32 v50, v50
	s_waitcnt lgkmcnt(0)
	v_add_f32_e32 v42, v52, v53
	ds_bpermute_b32 v43, v32, v42
	v_exp_f32_e32 v51, v51
	v_add_f32_e32 v50, 1.0, v50
	v_rcp_f32_e32 v50, v50
	v_pk_mul_f32 v[26:27], v[44:45], v[26:27]
	s_waitcnt lgkmcnt(0)
	v_add_f32_e32 v42, v42, v43
	ds_bpermute_b32 v43, v33, v42
	v_add_f32_e32 v51, 1.0, v51
	v_rcp_f32_e32 v51, v51
	v_pk_mul_f32 v[38:39], v[46:47], v[48:49]
	s_waitcnt lgkmcnt(0)
	v_add_f32_e32 v42, v42, v43
	ds_bpermute_b32 v43, v34, v42
	v_pk_mul_f32 v[24:25], v[50:51], v[24:25]
	s_waitcnt lgkmcnt(0)
	v_add_f32_e32 v42, v42, v43
	v_fmamk_f32 v42, v42, 0x3c000000, v35
	v_mul_f32_e32 v43, 0x4b800000, v42
	v_cmp_gt_f32_e32 vcc, s3, v42
	s_nop 1
	v_cndmask_b32_e32 v42, v42, v43, vcc
	v_rsq_f32_e32 v42, v42
	s_nop 0
	v_mul_f32_e32 v43, 0x45800000, v42
	v_cndmask_b32_e32 v42, v42, v43, vcc
	v_pk_mul_f32 v[10:11], v[10:11], v[42:43] op_sel_hi:[1,0]
	v_pk_mul_f32 v[36:37], v[36:37], v[42:43] op_sel_hi:[1,0]
	v_pk_mul_f32 v[12:13], v[12:13], v[42:43] op_sel_hi:[1,0]
	v_pk_mul_f32 v[28:29], v[28:29], v[42:43] op_sel_hi:[1,0]
	v_pk_mul_f32 v[10:11], v[2:3], v[10:11]
	v_pk_mul_f32 v[36:37], v[4:5], v[36:37]
	v_pk_mul_f32 v[12:13], v[6:7], v[12:13]
	v_pk_mul_f32 v[28:29], v[8:9], v[28:29]
	v_pk_mul_f32 v[10:11], v[24:25], v[10:11]
	v_pk_mul_f32 v[24:25], v[38:39], v[36:37]
	v_pk_mul_f32 v[12:13], v[26:27], v[12:13]
	v_pk_mul_f32 v[26:27], v[40:41], v[28:29]
	v_cvt_pk_bf16_f32 v10, v10, v11
	v_cvt_pk_bf16_f32 v11, v24, v25
	v_cvt_pk_bf16_f32 v12, v12, v13
	v_cvt_pk_bf16_f32 v13, v26, v27
	global_store_dwordx4 v[22:23], v[10:13], off offset:3072
	global_load_dwordx4 v[10:13], v[16:17], off offset:2048 nt
	s_nop 0
	global_load_dwordx4 v[22:25], v[18:19], off offset:2048 nt
	global_load_dwordx4 v[26:29], v[20:21], off offset:2048 nt
	s_waitcnt vmcnt(2)
	v_lshlrev_b32_e32 v36, 16, v13
	v_and_b32_e32 v37, 0xffff0000, v13
	s_waitcnt vmcnt(1)
	v_lshlrev_b32_e32 v38, 16, v25
	v_and_b32_e32 v39, 0xffff0000, v25
	s_waitcnt vmcnt(0)
	v_lshlrev_b32_e32 v40, 16, v29
	v_and_b32_e32 v41, 0xffff0000, v29
	v_lshlrev_b32_e32 v42, 16, v12
	v_and_b32_e32 v43, 0xffff0000, v12
	v_lshlrev_b32_e32 v12, 16, v24
	v_and_b32_e32 v13, 0xffff0000, v24
	v_lshlrev_b32_e32 v24, 16, v28
	v_and_b32_e32 v25, 0xffff0000, v28
	v_lshlrev_b32_e32 v28, 16, v11
	v_and_b32_e32 v29, 0xffff0000, v11
	v_lshlrev_b32_e32 v44, 16, v23
	v_and_b32_e32 v45, 0xffff0000, v23
	v_lshlrev_b32_e32 v46, 16, v27
	v_and_b32_e32 v47, 0xffff0000, v27
	v_lshlrev_b32_e32 v48, 16, v10
	v_and_b32_e32 v49, 0xffff0000, v10
	v_lshlrev_b32_e32 v10, 16, v22
	v_and_b32_e32 v11, 0xffff0000, v22
	v_pk_add_f32 v[12:13], v[42:43], v[12:13]
	v_mul_f32_e32 v42, 0xbfb8aa3b, v24
	v_mul_f32_e32 v43, 0xbfb8aa3b, v25
	v_pk_add_f32 v[28:29], v[28:29], v[44:45]
	v_mul_f32_e32 v44, 0xbfb8aa3b, v46
	v_mul_f32_e32 v45, 0xbfb8aa3b, v47
	v_pk_add_f32 v[10:11], v[48:49], v[10:11]
	v_exp_f32_e32 v52, v42
	v_exp_f32_e32 v53, v43
	v_exp_f32_e32 v54, v44
	v_exp_f32_e32 v55, v45
	v_pk_mul_f32 v[44:45], v[10:11], v[10:11]
	v_mul_f32_e32 v50, 0xbfb8aa3b, v40
	v_pk_mul_f32 v[42:43], v[28:29], v[28:29]
	v_add_f32_e32 v44, v44, v45
	v_mul_f32_e32 v51, 0xbfb8aa3b, v41
	v_exp_f32_e32 v50, v50
	v_add_f32_e32 v42, v42, v44
	v_lshlrev_b32_e32 v22, 16, v26
	v_and_b32_e32 v23, 0xffff0000, v26
	v_pk_add_f32 v[26:27], v[36:37], v[38:39]
	v_pk_mul_f32 v[38:39], v[12:13], v[12:13]
	v_exp_f32_e32 v51, v51
	v_add_f32_e32 v42, v43, v42
	v_add_f32_e32 v43, 1.0, v52
	v_add_f32_e32 v44, 1.0, v53
	v_add_f32_e32 v45, 1.0, v54
	v_add_f32_e32 v52, 1.0, v55
	v_add_f32_e32 v38, v38, v42
	v_pk_mul_f32 v[36:37], v[26:27], v[26:27]
	v_rcp_f32_e32 v42, v43
	v_rcp_f32_e32 v43, v44
	v_rcp_f32_e32 v44, v45
	v_rcp_f32_e32 v45, v52
	v_add_f32_e32 v52, v39, v38
	v_add_f32_e32 v50, 1.0, v50
	v_add_f32_e32 v36, v36, v52
	v_add_f32_e32 v51, 1.0, v51
	v_rcp_f32_e32 v38, v50
	v_add_f32_e32 v50, v37, v36
	v_rcp_f32_e32 v39, v51
	ds_bpermute_b32 v51, v31, v50
	v_mul_f32_e32 v48, 0xbfb8aa3b, v22
	v_mul_f32_e32 v49, 0xbfb8aa3b, v23
	v_pk_mul_f32 v[38:39], v[38:39], v[40:41]
	v_exp_f32_e32 v48, v48
	s_waitcnt lgkmcnt(0)
	v_add_f32_e32 v40, v50, v51
	ds_bpermute_b32 v41, v32, v40
	v_exp_f32_e32 v49, v49
	v_add_f32_e32 v48, 1.0, v48
	v_rcp_f32_e32 v48, v48
	v_pk_mul_f32 v[24:25], v[42:43], v[24:25]
	s_waitcnt lgkmcnt(0)
	v_add_f32_e32 v40, v40, v41
	ds_bpermute_b32 v41, v33, v40
	v_add_f32_e32 v49, 1.0, v49
	v_rcp_f32_e32 v49, v49
	v_pk_mul_f32 v[36:37], v[44:45], v[46:47]
	s_waitcnt lgkmcnt(0)
	v_add_f32_e32 v40, v40, v41
	ds_bpermute_b32 v41, v34, v40
	v_pk_mul_f32 v[22:23], v[48:49], v[22:23]
	s_waitcnt lgkmcnt(0)
	v_add_f32_e32 v40, v40, v41
	v_fmamk_f32 v40, v40, 0x3c000000, v35
	v_mul_f32_e32 v41, 0x4b800000, v40
	v_cmp_gt_f32_e32 vcc, s3, v40
	s_nop 1
	v_cndmask_b32_e32 v40, v40, v41, vcc
	v_rsq_f32_e32 v40, v40
	s_nop 0
	v_mul_f32_e32 v41, 0x45800000, v40
	v_cndmask_b32_e32 v40, v40, v41, vcc
	v_pk_mul_f32 v[10:11], v[10:11], v[40:41] op_sel_hi:[1,0]
	v_pk_mul_f32 v[28:29], v[28:29], v[40:41] op_sel_hi:[1,0]
	v_pk_mul_f32 v[12:13], v[12:13], v[40:41] op_sel_hi:[1,0]
	v_pk_mul_f32 v[26:27], v[26:27], v[40:41] op_sel_hi:[1,0]
	v_pk_mul_f32 v[10:11], v[2:3], v[10:11]
	v_pk_mul_f32 v[28:29], v[4:5], v[28:29]
	v_pk_mul_f32 v[12:13], v[6:7], v[12:13]
	v_pk_mul_f32 v[26:27], v[8:9], v[26:27]
	v_pk_mul_f32 v[10:11], v[22:23], v[10:11]
	v_pk_mul_f32 v[22:23], v[36:37], v[28:29]
	v_pk_mul_f32 v[12:13], v[24:25], v[12:13]
	v_pk_mul_f32 v[24:25], v[38:39], v[26:27]
	v_cvt_pk_bf16_f32 v10, v10, v11
	v_cvt_pk_bf16_f32 v11, v22, v23
	v_cvt_pk_bf16_f32 v12, v12, v13
	v_cvt_pk_bf16_f32 v13, v24, v25
	global_store_dwordx4 v[14:15], v[10:13], off offset:1024
	global_load_dwordx4 v[10:13], v[16:17], off offset:3072 nt
	s_nop 0
	global_load_dwordx4 v[22:25], v[18:19], off offset:3072 nt
	global_load_dwordx4 v[26:29], v[20:21], off offset:3072 nt
	s_waitcnt vmcnt(2)
	v_lshlrev_b32_e32 v16, 16, v13
	v_and_b32_e32 v17, 0xffff0000, v13
	s_waitcnt vmcnt(1)
	v_lshlrev_b32_e32 v18, 16, v25
	v_and_b32_e32 v19, 0xffff0000, v25
	s_waitcnt vmcnt(0)
	v_lshlrev_b32_e32 v20, 16, v29
	v_and_b32_e32 v21, 0xffff0000, v29
	v_lshlrev_b32_e32 v36, 16, v12
	v_and_b32_e32 v37, 0xffff0000, v12
	v_lshlrev_b32_e32 v12, 16, v24
	v_and_b32_e32 v13, 0xffff0000, v24
	v_lshlrev_b32_e32 v24, 16, v28
	v_and_b32_e32 v25, 0xffff0000, v28
	v_lshlrev_b32_e32 v28, 16, v11
	v_and_b32_e32 v29, 0xffff0000, v11
	v_lshlrev_b32_e32 v38, 16, v23
	v_and_b32_e32 v39, 0xffff0000, v23
	v_lshlrev_b32_e32 v40, 16, v27
	v_and_b32_e32 v41, 0xffff0000, v27
	v_lshlrev_b32_e32 v42, 16, v10
	v_and_b32_e32 v43, 0xffff0000, v10
	v_lshlrev_b32_e32 v10, 16, v22
	v_and_b32_e32 v11, 0xffff0000, v22
	v_pk_add_f32 v[16:17], v[16:17], v[18:19]
	v_pk_add_f32 v[12:13], v[36:37], v[12:13]
	v_mul_f32_e32 v36, 0xbfb8aa3b, v24
	v_mul_f32_e32 v37, 0xbfb8aa3b, v25
	v_pk_add_f32 v[18:19], v[28:29], v[38:39]
	v_mul_f32_e32 v38, 0xbfb8aa3b, v40
	v_mul_f32_e32 v39, 0xbfb8aa3b, v41
	v_pk_add_f32 v[10:11], v[42:43], v[10:11]
	v_exp_f32_e32 v46, v36
	v_exp_f32_e32 v47, v37
	v_exp_f32_e32 v48, v38
	v_exp_f32_e32 v49, v39
	v_pk_mul_f32 v[38:39], v[10:11], v[10:11]
	v_mul_f32_e32 v44, 0xbfb8aa3b, v20
	v_pk_mul_f32 v[36:37], v[18:19], v[18:19]
	v_add_f32_e32 v38, v38, v39
	v_mul_f32_e32 v45, 0xbfb8aa3b, v21
	v_exp_f32_e32 v44, v44
	v_add_f32_e32 v36, v36, v38
	v_pk_mul_f32 v[28:29], v[12:13], v[12:13]
	v_exp_f32_e32 v45, v45
	v_add_f32_e32 v36, v37, v36
	v_add_f32_e32 v37, 1.0, v46
	v_add_f32_e32 v38, 1.0, v47
	v_add_f32_e32 v39, 1.0, v48
	v_add_f32_e32 v46, 1.0, v49
	v_add_f32_e32 v28, v28, v36
	v_lshlrev_b32_e32 v22, 16, v26
	v_and_b32_e32 v23, 0xffff0000, v26
	v_pk_mul_f32 v[26:27], v[16:17], v[16:17]
	v_rcp_f32_e32 v36, v37
	v_rcp_f32_e32 v37, v38
	v_rcp_f32_e32 v38, v39
	v_rcp_f32_e32 v39, v46
	v_add_f32_e32 v46, v29, v28
	v_add_f32_e32 v44, 1.0, v44
	v_add_f32_e32 v26, v26, v46
	v_add_f32_e32 v45, 1.0, v45
	v_rcp_f32_e32 v28, v44
	v_add_f32_e32 v44, v27, v26
	v_rcp_f32_e32 v29, v45
	ds_bpermute_b32 v45, v31, v44
	v_mul_f32_e32 v42, 0xbfb8aa3b, v22
	v_mul_f32_e32 v43, 0xbfb8aa3b, v23
	v_pk_mul_f32 v[20:21], v[28:29], v[20:21]
	v_exp_f32_e32 v42, v42
	s_waitcnt lgkmcnt(0)
	v_add_f32_e32 v28, v44, v45
	ds_bpermute_b32 v29, v32, v28
	v_exp_f32_e32 v43, v43
	v_add_f32_e32 v42, 1.0, v42
	v_rcp_f32_e32 v42, v42
	v_pk_mul_f32 v[24:25], v[36:37], v[24:25]
	s_waitcnt lgkmcnt(0)
	v_add_f32_e32 v28, v28, v29
	ds_bpermute_b32 v29, v33, v28
	v_add_f32_e32 v43, 1.0, v43
	v_rcp_f32_e32 v43, v43
	v_pk_mul_f32 v[26:27], v[38:39], v[40:41]
	s_waitcnt lgkmcnt(0)
	v_add_f32_e32 v28, v28, v29
	ds_bpermute_b32 v29, v34, v28
	v_pk_mul_f32 v[22:23], v[42:43], v[22:23]
	s_waitcnt lgkmcnt(0)
	v_add_f32_e32 v28, v28, v29
	v_fmamk_f32 v28, v28, 0x3c000000, v35
	v_mul_f32_e32 v29, 0x4b800000, v28
	v_cmp_gt_f32_e32 vcc, s3, v28
	s_nop 1
	v_cndmask_b32_e32 v28, v28, v29, vcc
	v_rsq_f32_e32 v28, v28
	s_nop 0
	v_mul_f32_e32 v29, 0x45800000, v28
	v_cndmask_b32_e32 v28, v28, v29, vcc
	v_pk_mul_f32 v[10:11], v[10:11], v[28:29] op_sel_hi:[1,0]
	v_pk_mul_f32 v[18:19], v[18:19], v[28:29] op_sel_hi:[1,0]
	v_pk_mul_f32 v[12:13], v[12:13], v[28:29] op_sel_hi:[1,0]
	v_pk_mul_f32 v[16:17], v[16:17], v[28:29] op_sel_hi:[1,0]
	v_pk_mul_f32 v[10:11], v[2:3], v[10:11]
	v_pk_mul_f32 v[18:19], v[4:5], v[18:19]
	v_pk_mul_f32 v[12:13], v[6:7], v[12:13]
	v_pk_mul_f32 v[16:17], v[8:9], v[16:17]
	v_pk_mul_f32 v[10:11], v[22:23], v[10:11]
	v_pk_mul_f32 v[18:19], v[26:27], v[18:19]
	v_pk_mul_f32 v[12:13], v[24:25], v[12:13]
	v_pk_mul_f32 v[16:17], v[20:21], v[16:17]
	v_cvt_pk_bf16_f32 v10, v10, v11
	v_cvt_pk_bf16_f32 v11, v18, v19
	v_cvt_pk_bf16_f32 v12, v12, v13
	v_cvt_pk_bf16_f32 v13, v16, v17
	global_store_dwordx4 v[14:15], v[10:13], off offset:3072
	s_cbranch_scc0 .LBB0_524
	v_mov_b32_e32 v8, v0
	s_barrier
	s_mov_b32 s3, 0x1fffe0
	v_lshlrev_b32_e32 v2, 4, v8
	v_add_u32_e32 v3, 0x2000, v2
	v_ashrrev_i32_e32 v4, 31, v3
	v_lshrrev_b32_e32 v4, 22, v4
	v_add_u32_e32 v4, v3, v4
	v_ashrrev_i32_e32 v6, 10, v4
	v_mul_i32_i24_e32 v4, 0x400, v6
	v_sub_u32_e32 v3, v3, v4
	v_lshrrev_b32_e32 v4, 4, v3
	v_bitop3_b32 v3, v4, v3, 32 bitop3:0x6c
	v_ashrrev_i32_e32 v4, 31, v3
	v_lshrrev_b32_e32 v4, 26, v4
	v_add_u32_e32 v4, v3, v4
	v_lshlrev_b32_e32 v5, 3, v6
	v_ashrrev_i32_e32 v7, 6, v4
	v_and_b32_e32 v5, -16, v5
	v_add_u32_e32 v5, v7, v5
	v_and_b32_e32 v9, 3, v7
	v_lshrrev_b32_e32 v10, 2, v5
	v_lshlrev_b32_e32 v11, 1, v5
	v_and_b32_e32 v4, 0xc0, v4
	v_and_or_b32 v9, v5, s3, v9
	v_and_b32_e32 v10, 4, v10
	v_and_b32_e32 v11, 24, v11
	v_sub_u32_e32 v3, v3, v4
	v_mov_b32_e32 v4, 1
	v_or3_b32 v10, v9, v10, v11
	v_lshlrev_b32_e32 v9, 5, v6
	v_ashrrev_i16_sdwa v3, v4, sext(v3) dst_sel:DWORD dst_unused:UNUSED_PAD src0_sel:DWORD src1_sel:BYTE_0
	v_and_b32_e32 v11, 32, v9
	v_bfe_i32 v9, v3, 0, 16
	v_add_lshl_u32 v3, v11, v9, 1
	v_lshl_add_u32 v178, v10, 11, v3
	v_lshl_add_u32 v180, v5, 11, v3
	v_bfe_i32 v3, v8, 27, 1
	v_lshrrev_b32_e32 v3, 22, v3
	v_add_u32_e32 v3, v2, v3
	v_and_b32_e32 v3, 0xfffffc00, v3
	v_sub_u32_e32 v2, v2, v3
	v_lshrrev_b32_e32 v3, 4, v2
	v_ashrrev_i32_e32 v5, 31, v8
	v_bitop3_b32 v2, v3, v2, 32 bitop3:0x6c
	v_lshrrev_b32_e32 v5, 26, v5
	v_ashrrev_i32_e32 v3, 31, v2
	v_add_u32_e32 v5, v8, v5
	v_lshrrev_b32_e32 v3, 26, v3
	v_ashrrev_i32_e32 v11, 6, v5
	v_add_u32_e32 v3, v2, v3
	v_lshlrev_b32_e32 v5, 3, v11
	v_ashrrev_i32_e32 v10, 6, v3
	v_and_b32_e32 v5, -16, v5
	v_add_u32_e32 v5, v10, v5
	v_and_b32_e32 v12, 3, v10
	v_lshrrev_b32_e32 v13, 2, v5
	v_lshlrev_b32_e32 v14, 1, v5
	v_and_b32_e32 v3, 0xc0, v3
	v_readfirstlane_b32 s2, v8
	v_and_or_b32 v12, v5, s3, v12
	v_and_b32_e32 v13, 4, v13
	v_and_b32_e32 v14, 24, v14
	v_sub_u32_e32 v2, v2, v3
	s_ashr_i32 s0, s2, 6
	v_or3_b32 v13, v12, v13, v14
	v_lshlrev_b32_e32 v12, 5, v11
	v_ashrrev_i16_sdwa v2, v4, sext(v2) dst_sel:DWORD dst_unused:UNUSED_PAD src0_sel:DWORD src1_sel:BYTE_0
	s_lshl_b32 s12, s0, 10
	v_and_b32_e32 v14, 32, v12
	v_bfe_i32 v12, v2, 0, 16
	v_add_lshl_u32 v2, v14, v12, 1
	s_add_i32 s3, s12, 0
	v_lshl_add_u32 v182, v13, 11, v2
	s_add_i32 m0, s3, 0x10000
	s_ashr_i32 s1, s2, 8
	global_load_lds_dwordx4 v182, s[88:89]
	s_add_i32 m0, s3, 0x12000
	s_add_u32 s6, s80, s8
	v_lshl_add_u32 v190, v5, 11, v2
	global_load_lds_dwordx4 v178, s[88:89]
	s_addc_u32 s7, s81, s9
	s_mov_b32 m0, s3
	s_add_i32 s20, s3, 0x2000
	global_load_lds_dwordx4 v190, s[6:7]
	s_mov_b32 m0, s20
	s_add_u32 s14, s80, 0x36940000
	global_load_lds_dwordx4 v180, s[6:7]
	s_addc_u32 s15, s81, 0
	s_add_i32 m0, s3, 0x14000
	v_mov_b32_e32 v183, 0
	global_load_lds_dwordx4 v182, s[14:15]
	s_add_i32 m0, s3, 0x16000
	v_mov_b32_e32 v191, v183
	global_load_lds_dwordx4 v178, s[14:15]
	s_add_u32 s14, s6, 0x40000
	s_addc_u32 s15, s7, 0
	s_add_i32 s21, s3, 0x4000
	s_mov_b32 m0, s21
	s_add_i32 s22, s3, 0x6000
	global_load_lds_dwordx4 v190, s[14:15]
	s_mov_b32 m0, s22
	v_mov_b32_e32 v181, v183
	global_load_lds_dwordx4 v180, s[14:15]
	s_mov_b32 s23, 0
	v_mov_b32_e32 v179, v183
	v_lshl_add_u64 v[4:5], s[6:7], 0, v[190:191]
	s_cmp_lg_u32 s1, 1
	v_lshl_add_u64 v[2:3], s[6:7], 0, v[180:181]
	s_cbranch_scc1 .LBB0_527
	s_barrier

.LBB0_530:
	s_add_u32 s16, s6, s14
	ds_read_b128 v[130:133], v1
	ds_read_b128 v[134:137], v1 offset:1024
	ds_read_b128 v[138:141], v1 offset:2048
	ds_read_b128 v[142:145], v1 offset:3072
	s_addc_u32 s17, s7, s15
	s_add_u32 s16, s16, 0x100
	s_addc_u32 s17, s17, 0
	s_add_u32 s55, s52, s14
	s_addc_u32 s56, s53, s15
	s_cmpk_eq_i32 s14, 0x700
	s_cselect_b32 s19, s7, s17
	s_cselect_b32 s18, s6, s16
	s_cselect_b32 s17, s50, s56
	s_cselect_b32 s16, s51, s55
	s_mov_b32 m0, s34
	v_lshl_add_u64 v[196:197], v[192:193], 0, s[14:15]
	ds_read_b128 v[146:149], v210
	ds_read_b128 v[150:153], v210 offset:1024
	ds_read_b128 v[154:157], v210 offset:2048
	ds_read_b128 v[158:161], v210 offset:3072
	ds_read_b128 v[162:165], v210 offset:4096
	ds_read_b128 v[166:169], v210 offset:5120
	ds_read_b128 v[170:173], v210 offset:6144
	ds_read_b128 v[174:177], v210 offset:7168
	global_load_lds_dwordx4 v[196:197], off
	v_lshl_add_u64 v[196:197], v[194:195], 0, s[14:15]
	s_mov_b32 m0, s35
	s_nop 0
	global_load_lds_dwordx4 v[196:197], off
	s_waitcnt lgkmcnt(8)
	s_barrier
	s_waitcnt lgkmcnt(0)
	s_setprio 1
	s_waitcnt lgkmcnt(0)
	v_mfma_f32_16x16x32_bf16 v[126:129], v[130:133], v[146:149], v[126:129]
	v_mfma_f32_16x16x32_bf16 v[122:125], v[138:141], v[146:149], v[122:125]
	v_mfma_f32_16x16x32_bf16 v[110:113], v[130:133], v[154:157], v[110:113]
	v_mfma_f32_16x16x32_bf16 v[106:109], v[138:141], v[154:157], v[106:109]
	v_mfma_f32_16x16x32_bf16 v[94:97], v[130:133], v[162:165], v[94:97]
	v_mfma_f32_16x16x32_bf16 v[90:93], v[138:141], v[162:165], v[90:93]
	v_mfma_f32_16x16x32_bf16 v[78:81], v[130:133], v[170:173], v[78:81]
	v_mfma_f32_16x16x32_bf16 v[74:77], v[138:141], v[170:173], v[74:77]
	v_mfma_f32_16x16x32_bf16 v[126:129], v[134:137], v[150:153], v[126:129]
	v_mfma_f32_16x16x32_bf16 v[122:125], v[142:145], v[150:153], v[122:125]
	v_mfma_f32_16x16x32_bf16 v[110:113], v[134:137], v[158:161], v[110:113]
	v_mfma_f32_16x16x32_bf16 v[106:109], v[142:145], v[158:161], v[106:109]
	v_mfma_f32_16x16x32_bf16 v[94:97], v[134:137], v[166:169], v[94:97]
	v_mfma_f32_16x16x32_bf16 v[90:93], v[142:145], v[166:169], v[90:93]
	v_mfma_f32_16x16x32_bf16 v[78:81], v[134:137], v[174:177], v[78:81]
	v_mfma_f32_16x16x32_bf16 v[74:77], v[142:145], v[174:177], v[74:77]
	s_setprio 0
	s_barrier
	s_mov_b32 m0, s36
	v_lshl_add_u64 v[218:219], s[16:17], 0, v[182:183]
	ds_read_b128 v[196:199], v211
	ds_read_b128 v[200:203], v211 offset:1024
	ds_read_b128 v[204:207], v211 offset:2048
	ds_read_b128 v[214:217], v211 offset:3072
	global_load_lds_dwordx4 v[218:219], off
	v_lshl_add_u64 v[220:221], s[16:17], 0, v[178:179]
	s_mov_b32 m0, s37
	s_nop 0
	global_load_lds_dwordx4 v[220:221], off
	s_barrier
	s_waitcnt lgkmcnt(0)
	s_setprio 1
	s_waitcnt lgkmcnt(0)
	v_mfma_f32_16x16x32_bf16 v[118:121], v[196:199], v[146:149], v[118:121]
	v_mfma_f32_16x16x32_bf16 v[114:117], v[204:207], v[146:149], v[114:117]
	v_mfma_f32_16x16x32_bf16 v[102:105], v[196:199], v[154:157], v[102:105]
	v_mfma_f32_16x16x32_bf16 v[98:101], v[204:207], v[154:157], v[98:101]
	v_mfma_f32_16x16x32_bf16 v[86:89], v[196:199], v[162:165], v[86:89]
	v_mfma_f32_16x16x32_bf16 v[82:85], v[204:207], v[162:165], v[82:85]
	v_mfma_f32_16x16x32_bf16 v[70:73], v[196:199], v[170:173], v[70:73]
	v_mfma_f32_16x16x32_bf16 v[66:69], v[204:207], v[170:173], v[66:69]
	v_mfma_f32_16x16x32_bf16 v[118:121], v[200:203], v[150:153], v[118:121]
	v_mfma_f32_16x16x32_bf16 v[114:117], v[214:217], v[150:153], v[114:117]
	v_mfma_f32_16x16x32_bf16 v[102:105], v[200:203], v[158:161], v[102:105]
	v_mfma_f32_16x16x32_bf16 v[98:101], v[214:217], v[158:161], v[98:101]
	v_mfma_f32_16x16x32_bf16 v[86:89], v[200:203], v[166:169], v[86:89]
	v_mfma_f32_16x16x32_bf16 v[82:85], v[214:217], v[166:169], v[82:85]
	v_mfma_f32_16x16x32_bf16 v[70:73], v[200:203], v[174:177], v[70:73]
	v_mfma_f32_16x16x32_bf16 v[66:69], v[214:217], v[174:177], v[66:69]
	s_setprio 0
	s_mov_b32 m0, s3
	v_lshl_add_u64 v[222:223], s[18:19], 0, v[190:191]
	s_barrier
	ds_read_b128 v[146:149], v210 offset:16384
	ds_read_b128 v[150:153], v210 offset:17408
	ds_read_b128 v[154:157], v210 offset:18432
	ds_read_b128 v[158:161], v210 offset:19456
	ds_read_b128 v[162:165], v210 offset:20480
	ds_read_b128 v[166:169], v210 offset:21504
	ds_read_b128 v[170:173], v210 offset:22528
	ds_read_b128 v[174:177], v210 offset:23552
	global_load_lds_dwordx4 v[222:223], off
	v_lshl_add_u64 v[224:225], s[18:19], 0, v[180:181]
	s_mov_b32 m0, s20
	s_nop 0
	global_load_lds_dwordx4 v[224:225], off
	s_barrier
	s_waitcnt lgkmcnt(0)
	s_setprio 1
	s_waitcnt lgkmcnt(0)
	v_mfma_f32_16x16x32_bf16 v[62:65], v[130:133], v[146:149], v[62:65]
	v_mfma_f32_16x16x32_bf16 v[58:61], v[138:141], v[146:149], v[58:61]
	v_mfma_f32_16x16x32_bf16 v[46:49], v[130:133], v[154:157], v[46:49]
	v_mfma_f32_16x16x32_bf16 v[42:45], v[138:141], v[154:157], v[42:45]
	v_mfma_f32_16x16x32_bf16 v[30:33], v[130:133], v[162:165], v[30:33]
	v_mfma_f32_16x16x32_bf16 v[26:29], v[138:141], v[162:165], v[26:29]
	v_mfma_f32_16x16x32_bf16 v[14:17], v[130:133], v[170:173], v[14:17]
	v_mfma_f32_16x16x32_bf16 v[10:13], v[138:141], v[170:173], v[10:13]
	v_mfma_f32_16x16x32_bf16 v[62:65], v[134:137], v[150:153], v[62:65]
	v_mfma_f32_16x16x32_bf16 v[58:61], v[142:145], v[150:153], v[58:61]
	v_mfma_f32_16x16x32_bf16 v[46:49], v[134:137], v[158:161], v[46:49]
	v_mfma_f32_16x16x32_bf16 v[42:45], v[142:145], v[158:161], v[42:45]
	v_mfma_f32_16x16x32_bf16 v[30:33], v[134:137], v[166:169], v[30:33]
	v_mfma_f32_16x16x32_bf16 v[26:29], v[142:145], v[166:169], v[26:29]
	v_mfma_f32_16x16x32_bf16 v[14:17], v[134:137], v[174:177], v[14:17]
	v_mfma_f32_16x16x32_bf16 v[10:13], v[142:145], v[174:177], v[10:13]
	s_setprio 0
	s_barrier
	s_add_u32 s56, s16, 0x40000
	s_addc_u32 s57, s17, 0
	s_mov_b32 m0, s38
	v_lshl_add_u64 v[130:131], s[56:57], 0, v[182:183]
	global_load_lds_dwordx4 v[130:131], off
	v_lshl_add_u64 v[130:131], s[56:57], 0, v[178:179]
	s_mov_b32 m0, s39
	s_nop 0
	global_load_lds_dwordx4 v[130:131], off
	s_waitcnt vmcnt(6)
	s_barrier
	s_setprio 1
	v_mfma_f32_16x16x32_bf16 v[54:57], v[196:199], v[146:149], v[54:57]
	v_mfma_f32_16x16x32_bf16 v[50:53], v[204:207], v[146:149], v[50:53]
	v_mfma_f32_16x16x32_bf16 v[38:41], v[196:199], v[154:157], v[38:41]
	v_mfma_f32_16x16x32_bf16 v[34:37], v[204:207], v[154:157], v[34:37]
	v_mfma_f32_16x16x32_bf16 v[22:25], v[196:199], v[162:165], v[22:25]
	v_mfma_f32_16x16x32_bf16 v[18:21], v[204:207], v[162:165], v[18:21]
	v_mfma_f32_16x16x32_bf16 v[6:9], v[196:199], v[170:173], v[6:9]
	v_mfma_f32_16x16x32_bf16 v[2:5], v[204:207], v[170:173], v[2:5]
	v_mfma_f32_16x16x32_bf16 v[54:57], v[200:203], v[150:153], v[54:57]
	v_mfma_f32_16x16x32_bf16 v[50:53], v[214:217], v[150:153], v[50:53]
	v_mfma_f32_16x16x32_bf16 v[38:41], v[200:203], v[158:161], v[38:41]
	v_mfma_f32_16x16x32_bf16 v[34:37], v[214:217], v[158:161], v[34:37]
	v_mfma_f32_16x16x32_bf16 v[22:25], v[200:203], v[166:169], v[22:25]
	v_mfma_f32_16x16x32_bf16 v[18:21], v[214:217], v[166:169], v[18:21]
	v_mfma_f32_16x16x32_bf16 v[6:9], v[200:203], v[174:177], v[6:9]
	v_mfma_f32_16x16x32_bf16 v[2:5], v[214:217], v[174:177], v[2:5]
	s_setprio 0
	s_barrier
	ds_read_b128 v[130:133], v212
	ds_read_b128 v[134:137], v212 offset:1024
	ds_read_b128 v[138:141], v212 offset:2048
	ds_read_b128 v[142:145], v212 offset:3072
	s_add_u32 s18, s18, 0x40000
	s_addc_u32 s19, s19, 0
	s_mov_b32 m0, s21
	v_lshl_add_u64 v[196:197], s[18:19], 0, v[190:191]
	ds_read_b128 v[146:149], v210 offset:32768
	ds_read_b128 v[150:153], v210 offset:33792
	ds_read_b128 v[154:157], v210 offset:34816
	ds_read_b128 v[158:161], v210 offset:35840
	ds_read_b128 v[162:165], v210 offset:36864
	ds_read_b128 v[166:169], v210 offset:37888
	ds_read_b128 v[170:173], v210 offset:38912
	ds_read_b128 v[174:177], v210 offset:39936
	global_load_lds_dwordx4 v[196:197], off
	v_lshl_add_u64 v[196:197], s[18:19], 0, v[180:181]
	s_mov_b32 m0, s22
	s_nop 0
	global_load_lds_dwordx4 v[196:197], off
	s_waitcnt lgkmcnt(8)
	s_barrier
	s_waitcnt lgkmcnt(0)
	s_setprio 1
	s_waitcnt lgkmcnt(0)
	v_mfma_f32_16x16x32_bf16 v[126:129], v[130:133], v[146:149], v[126:129]
	v_mfma_f32_16x16x32_bf16 v[122:125], v[138:141], v[146:149], v[122:125]
	v_mfma_f32_16x16x32_bf16 v[110:113], v[130:133], v[154:157], v[110:113]
	v_mfma_f32_16x16x32_bf16 v[106:109], v[138:141], v[154:157], v[106:109]
	v_mfma_f32_16x16x32_bf16 v[94:97], v[130:133], v[162:165], v[94:97]
	v_mfma_f32_16x16x32_bf16 v[90:93], v[138:141], v[162:165], v[90:93]
	v_mfma_f32_16x16x32_bf16 v[78:81], v[130:133], v[170:173], v[78:81]
	v_mfma_f32_16x16x32_bf16 v[74:77], v[138:141], v[170:173], v[74:77]
	v_mfma_f32_16x16x32_bf16 v[126:129], v[134:137], v[150:153], v[126:129]
	v_mfma_f32_16x16x32_bf16 v[122:125], v[142:145], v[150:153], v[122:125]
	v_mfma_f32_16x16x32_bf16 v[110:113], v[134:137], v[158:161], v[110:113]
	v_mfma_f32_16x16x32_bf16 v[106:109], v[142:145], v[158:161], v[106:109]
	v_mfma_f32_16x16x32_bf16 v[94:97], v[134:137], v[166:169], v[94:97]
	v_mfma_f32_16x16x32_bf16 v[90:93], v[142:145], v[166:169], v[90:93]
	v_mfma_f32_16x16x32_bf16 v[78:81], v[134:137], v[174:177], v[78:81]
	v_mfma_f32_16x16x32_bf16 v[74:77], v[142:145], v[174:177], v[74:77]
	s_setprio 0
	s_barrier
	s_mov_b32 m0, s40
	v_lshl_add_u64 v[218:219], v[218:219], 0, s[0:1]
	ds_read_b128 v[196:199], v213
	ds_read_b128 v[200:203], v213 offset:1024
	ds_read_b128 v[204:207], v213 offset:2048
	ds_read_b128 v[214:217], v213 offset:3072
	global_load_lds_dwordx4 v[218:219], off
	v_lshl_add_u64 v[218:219], v[220:221], 0, s[0:1]
	s_mov_b32 m0, s41
	s_nop 0
	global_load_lds_dwordx4 v[218:219], off
	s_barrier
	s_waitcnt lgkmcnt(0)
	s_setprio 1
	s_waitcnt lgkmcnt(0)
	v_mfma_f32_16x16x32_bf16 v[118:121], v[196:199], v[146:149], v[118:121]
	v_mfma_f32_16x16x32_bf16 v[114:117], v[204:207], v[146:149], v[114:117]
	v_mfma_f32_16x16x32_bf16 v[102:105], v[196:199], v[154:157], v[102:105]
	v_mfma_f32_16x16x32_bf16 v[98:101], v[204:207], v[154:157], v[98:101]
	v_mfma_f32_16x16x32_bf16 v[86:89], v[196:199], v[162:165], v[86:89]
	v_mfma_f32_16x16x32_bf16 v[82:85], v[204:207], v[162:165], v[82:85]
	v_mfma_f32_16x16x32_bf16 v[70:73], v[196:199], v[170:173], v[70:73]
	v_mfma_f32_16x16x32_bf16 v[66:69], v[204:207], v[170:173], v[66:69]
	v_mfma_f32_16x16x32_bf16 v[118:121], v[200:203], v[150:153], v[118:121]
	v_mfma_f32_16x16x32_bf16 v[114:117], v[214:217], v[150:153], v[114:117]
	v_mfma_f32_16x16x32_bf16 v[102:105], v[200:203], v[158:161], v[102:105]
	v_mfma_f32_16x16x32_bf16 v[98:101], v[214:217], v[158:161], v[98:101]
	v_mfma_f32_16x16x32_bf16 v[86:89], v[200:203], v[166:169], v[86:89]
	v_mfma_f32_16x16x32_bf16 v[82:85], v[214:217], v[166:169], v[82:85]
	v_mfma_f32_16x16x32_bf16 v[70:73], v[200:203], v[174:177], v[70:73]
	v_mfma_f32_16x16x32_bf16 v[66:69], v[214:217], v[174:177], v[66:69]
	s_setprio 0
	s_mov_b32 m0, s30
	v_lshl_add_u64 v[218:219], v[222:223], 0, s[0:1]
	s_barrier
	ds_read_b128 v[146:149], v210 offset:49152
	ds_read_b128 v[150:153], v210 offset:50176
	ds_read_b128 v[154:157], v210 offset:51200
	ds_read_b128 v[158:161], v210 offset:52224
	ds_read_b128 v[162:165], v210 offset:53248
	ds_read_b128 v[166:169], v210 offset:54272
	ds_read_b128 v[170:173], v210 offset:55296
	ds_read_b128 v[174:177], v210 offset:56320
	global_load_lds_dwordx4 v[218:219], off
	v_lshl_add_u64 v[218:219], v[224:225], 0, s[0:1]
	s_mov_b32 m0, s31
	s_nop 0
	global_load_lds_dwordx4 v[218:219], off
	s_barrier
	s_waitcnt lgkmcnt(0)
	s_setprio 1
	s_waitcnt lgkmcnt(0)
	v_mfma_f32_16x16x32_bf16 v[62:65], v[130:133], v[146:149], v[62:65]
	v_mfma_f32_16x16x32_bf16 v[58:61], v[138:141], v[146:149], v[58:61]
	v_mfma_f32_16x16x32_bf16 v[46:49], v[130:133], v[154:157], v[46:49]
	v_mfma_f32_16x16x32_bf16 v[42:45], v[138:141], v[154:157], v[42:45]
	v_mfma_f32_16x16x32_bf16 v[30:33], v[130:133], v[162:165], v[30:33]
	v_mfma_f32_16x16x32_bf16 v[26:29], v[138:141], v[162:165], v[26:29]
	v_mfma_f32_16x16x32_bf16 v[14:17], v[130:133], v[170:173], v[14:17]
	v_mfma_f32_16x16x32_bf16 v[10:13], v[138:141], v[170:173], v[10:13]
	v_mfma_f32_16x16x32_bf16 v[62:65], v[134:137], v[150:153], v[62:65]
	v_mfma_f32_16x16x32_bf16 v[58:61], v[142:145], v[150:153], v[58:61]
	v_mfma_f32_16x16x32_bf16 v[46:49], v[134:137], v[158:161], v[46:49]
	v_mfma_f32_16x16x32_bf16 v[42:45], v[142:145], v[158:161], v[42:45]
	v_mfma_f32_16x16x32_bf16 v[30:33], v[134:137], v[166:169], v[30:33]
	v_mfma_f32_16x16x32_bf16 v[26:29], v[142:145], v[166:169], v[26:29]
	v_mfma_f32_16x16x32_bf16 v[14:17], v[134:137], v[174:177], v[14:17]
	v_mfma_f32_16x16x32_bf16 v[10:13], v[142:145], v[174:177], v[10:13]
	s_setprio 0
	s_barrier
	s_add_u32 s16, s16, 0x40080
	s_addc_u32 s17, s17, 0
	s_mov_b32 m0, s42
	v_lshl_add_u64 v[130:131], s[16:17], 0, v[182:183]
	global_load_lds_dwordx4 v[130:131], off
	v_lshl_add_u64 v[130:131], s[16:17], 0, v[178:179]
	s_mov_b32 m0, s43
	s_nop 0
	global_load_lds_dwordx4 v[130:131], off
	s_waitcnt vmcnt(6)
	s_barrier
	s_setprio 1
	v_mfma_f32_16x16x32_bf16 v[54:57], v[196:199], v[146:149], v[54:57]
	v_mfma_f32_16x16x32_bf16 v[50:53], v[204:207], v[146:149], v[50:53]
	v_mfma_f32_16x16x32_bf16 v[38:41], v[196:199], v[154:157], v[38:41]
	v_mfma_f32_16x16x32_bf16 v[34:37], v[204:207], v[154:157], v[34:37]
	v_mfma_f32_16x16x32_bf16 v[22:25], v[196:199], v[162:165], v[22:25]
	v_mfma_f32_16x16x32_bf16 v[18:21], v[204:207], v[162:165], v[18:21]
	v_mfma_f32_16x16x32_bf16 v[6:9], v[196:199], v[170:173], v[6:9]
	v_mfma_f32_16x16x32_bf16 v[2:5], v[204:207], v[170:173], v[2:5]
	v_mfma_f32_16x16x32_bf16 v[54:57], v[200:203], v[150:153], v[54:57]
	v_mfma_f32_16x16x32_bf16 v[50:53], v[214:217], v[150:153], v[50:53]
	v_mfma_f32_16x16x32_bf16 v[38:41], v[200:203], v[158:161], v[38:41]
	v_mfma_f32_16x16x32_bf16 v[34:37], v[214:217], v[158:161], v[34:37]
	v_mfma_f32_16x16x32_bf16 v[22:25], v[200:203], v[166:169], v[22:25]
	v_mfma_f32_16x16x32_bf16 v[18:21], v[214:217], v[166:169], v[18:21]
	v_mfma_f32_16x16x32_bf16 v[6:9], v[200:203], v[174:177], v[6:9]
	v_mfma_f32_16x16x32_bf16 v[2:5], v[214:217], v[174:177], v[2:5]
	s_setprio 0
	s_add_i32 s54, s54, 2
	s_add_u32 s14, s14, 0x100
	s_addc_u32 s15, s15, 0
	s_cmp_gt_u32 s54, 13
	s_barrier
	s_cbranch_scc0 .LBB0_530
	v_mov_b32_e32 v130, v208
	v_mov_b32_e32 v215, v209
	s_lshl_b32 s14, s49, 8
	s_or_b32 s14, s14, s29
	v_add_u32_e32 v214, s28, v130
	v_add_u32_e32 v200, s44, v214
	v_lshl_add_u32 v196, v215, 3, s14
	v_ashrrev_i32_e32 v197, 31, v196
	v_ashrrev_i32_e32 v201, 31, v200
	v_lshl_add_u64 v[198:199], v[196:197], 2, s[60:61]
	v_lshlrev_b64 v[130:131], 12, v[200:201]
	v_lshl_add_u64 v[130:131], v[198:199], 0, v[130:131]
	global_load_dwordx4 v[216:219], v[130:131], off nt
	global_load_dwordx4 v[220:223], v[130:131], off offset:16 nt
	global_load_dwordx4 v[224:227], v[130:131], off offset:512 nt
	global_load_dwordx4 v[228:231], v[130:131], off offset:528 nt
	v_add_u32_e32 v206, 16, v200
	v_add_u32_e32 v204, 32, v200
	v_add_u32_e32 v202, 48, v200
	v_ashrrev_i32_e32 v207, 31, v206
	v_ashrrev_i32_e32 v205, 31, v204
	v_ashrrev_i32_e32 v203, 31, v202
	v_lshlrev_b64 v[130:131], 12, v[206:207]
	v_lshlrev_b64 v[132:133], 12, v[204:205]
	v_lshlrev_b64 v[134:135], 12, v[202:203]
	v_lshl_add_u64 v[130:131], v[198:199], 0, v[130:131]
	v_lshl_add_u64 v[132:133], v[198:199], 0, v[132:133]
	v_lshl_add_u64 v[134:135], v[198:199], 0, v[134:135]
	global_load_dwordx4 v[170:173], v[130:131], off offset:16 nt
	global_load_dwordx4 v[174:177], v[130:131], off nt
	global_load_dwordx4 v[162:165], v[130:131], off offset:528 nt
	global_load_dwordx4 v[166:169], v[130:131], off offset:512 nt
	global_load_dwordx4 v[154:157], v[132:133], off offset:16 nt
	global_load_dwordx4 v[158:161], v[132:133], off nt
	global_load_dwordx4 v[146:149], v[132:133], off offset:528 nt
	global_load_dwordx4 v[150:153], v[132:133], off offset:512 nt
	global_load_dwordx4 v[138:141], v[134:135], off offset:16 nt
	global_load_dwordx4 v[142:145], v[134:135], off nt
	s_nop 0
	global_load_dwordx4 v[130:133], v[134:135], off offset:528 nt
	s_nop 0
	global_load_dwordx4 v[134:137], v[134:135], off offset:512 nt
	v_lshlrev_b64 v[232:233], 11, v[200:201]
	v_cmp_eq_u32_e32 vcc, 0, v215
	s_waitcnt vmcnt(0)
	v_pk_add_f32 v[126:127], v[126:127], v[216:217]
	v_pk_add_f32 v[128:129], v[128:129], v[218:219]
	v_pk_add_f32 v[118:119], v[118:119], v[224:225]
	v_pk_add_f32 v[218:219], v[114:115], v[228:229]
	v_cvt_pk_bf16_f32 v114, v126, v127
	v_mul_f32_e32 v127, v127, v127
	v_mul_f32_e32 v201, v119, v119
	v_pk_add_f32 v[120:121], v[120:121], v[226:227]
	v_fmac_f32_e32 v127, v126, v126
	v_fmac_f32_e32 v201, v118, v118
	v_fmac_f32_e32 v127, v128, v128
	v_fmac_f32_e32 v201, v120, v120
	v_pk_add_f32 v[122:123], v[122:123], v[220:221]
	v_fmac_f32_e32 v127, v129, v129
	v_fmac_f32_e32 v201, v121, v121
	v_fmac_f32_e32 v127, v122, v122
	v_fmac_f32_e32 v201, v218, v218
	v_pk_add_f32 v[124:125], v[124:125], v[222:223]
	v_pk_add_f32 v[216:217], v[116:117], v[230:231]
	v_fmac_f32_e32 v127, v123, v123
	v_fmac_f32_e32 v201, v219, v219
	v_fmac_f32_e32 v127, v124, v124
	v_fmac_f32_e32 v201, v216, v216
	v_fmac_f32_e32 v127, v125, v125
	v_fmac_f32_e32 v201, v217, v217
	v_cvt_pk_bf16_f32 v117, v124, v125
	v_add_f32_e32 v124, v127, v201
	ds_bpermute_b32 v125, v187, v124
	v_cvt_pk_bf16_f32 v116, v122, v123
	v_lshl_add_u64 v[122:123], s[26:27], 0, v[232:233]
	v_cvt_pk_bf16_f32 v115, v128, v129
	v_lshl_add_u64 v[122:123], v[196:197], 1, v[122:123]
	global_store_dwordx4 v[122:123], v[114:117], off
	s_waitcnt lgkmcnt(0)
	s_nop 0
	v_add_f32_e32 v114, v124, v125
	ds_bpermute_b32 v115, v189, v114
	v_cvt_pk_bf16_f32 v116, v118, v119
	v_cvt_pk_bf16_f32 v117, v120, v121
	v_cvt_pk_bf16_f32 v118, v218, v219
	v_cvt_pk_bf16_f32 v119, v216, v217
	global_store_dwordx4 v[122:123], v[116:119], off offset:256
	s_and_saveexec_b64 s[14:15], vcc
	s_cbranch_execz .LBB0_533
	s_waitcnt lgkmcnt(0)
	v_add_f32_e32 v114, v114, v115
	v_lshl_add_u32 v115, v214, 2, 0
	v_add_u32_e32 v115, 0x20000, v115
	ds_add_f32 v115, v114

.LBB0_539:
	s_or_b64 exec, exec, s[14:15]
	v_add_u32_e32 v136, 0x80, v200
	v_ashrrev_i32_e32 v137, 31, v136
	s_waitcnt lgkmcnt(0)
	v_lshlrev_b64 v[66:67], 12, v[136:137]
	v_lshl_add_u64 v[66:67], v[198:199], 0, v[66:67]
	global_load_dwordx4 v[120:123], v[66:67], off nt
	global_load_dwordx4 v[124:127], v[66:67], off offset:16 nt
	global_load_dwordx4 v[128:131], v[66:67], off offset:512 nt
	global_load_dwordx4 v[132:135], v[66:67], off offset:528 nt
	v_add_u32_e32 v118, 0x90, v200
	v_add_u32_e32 v116, 0xa0, v200
	v_add_u32_e32 v114, 0xb0, v200
	v_ashrrev_i32_e32 v119, 31, v118
	v_ashrrev_i32_e32 v117, 31, v116
	v_ashrrev_i32_e32 v115, 31, v114
	v_lshlrev_b64 v[66:67], 12, v[118:119]
	v_lshlrev_b64 v[68:69], 12, v[116:117]
	v_lshlrev_b64 v[70:71], 12, v[114:115]
	v_lshl_add_u64 v[66:67], v[198:199], 0, v[66:67]
	v_lshl_add_u64 v[68:69], v[198:199], 0, v[68:69]
	v_lshl_add_u64 v[70:71], v[198:199], 0, v[70:71]
	global_load_dwordx4 v[106:109], v[66:67], off offset:16 nt
	global_load_dwordx4 v[110:113], v[66:67], off nt
	global_load_dwordx4 v[98:101], v[66:67], off offset:528 nt
	global_load_dwordx4 v[102:105], v[66:67], off offset:512 nt
	global_load_dwordx4 v[90:93], v[68:69], off offset:16 nt
	global_load_dwordx4 v[94:97], v[68:69], off nt
	global_load_dwordx4 v[82:85], v[68:69], off offset:528 nt
	global_load_dwordx4 v[86:89], v[68:69], off offset:512 nt
	global_load_dwordx4 v[74:77], v[70:71], off offset:16 nt
	global_load_dwordx4 v[78:81], v[70:71], off nt
	s_nop 0
	global_load_dwordx4 v[66:69], v[70:71], off offset:528 nt
	s_nop 0
	global_load_dwordx4 v[70:73], v[70:71], off offset:512 nt
	v_lshlrev_b64 v[136:137], 11, v[136:137]
	s_waitcnt vmcnt(15)
	v_pk_add_f32 v[62:63], v[62:63], v[120:121]
	v_pk_add_f32 v[64:65], v[64:65], v[122:123]
	s_waitcnt vmcnt(13)
	v_pk_add_f32 v[54:55], v[54:55], v[128:129]
	v_pk_add_f32 v[58:59], v[58:59], v[124:125]
	s_waitcnt vmcnt(12)
	v_pk_add_f32 v[122:123], v[50:51], v[132:133]
	v_cvt_pk_bf16_f32 v50, v62, v63
	v_mul_f32_e32 v63, v63, v63
	v_mul_f32_e32 v124, v55, v55
	v_pk_add_f32 v[56:57], v[56:57], v[130:131]
	v_fmac_f32_e32 v63, v62, v62
	v_fmac_f32_e32 v124, v54, v54
	v_fmac_f32_e32 v63, v64, v64
	v_fmac_f32_e32 v124, v56, v56
	v_fmac_f32_e32 v63, v65, v65
	v_fmac_f32_e32 v124, v57, v57
	v_fmac_f32_e32 v63, v58, v58
	v_fmac_f32_e32 v124, v122, v122
	v_pk_add_f32 v[60:61], v[60:61], v[126:127]
	v_pk_add_f32 v[120:121], v[52:53], v[134:135]
	v_fmac_f32_e32 v63, v59, v59
	v_fmac_f32_e32 v124, v123, v123
	v_fmac_f32_e32 v63, v60, v60
	v_fmac_f32_e32 v124, v120, v120
	v_fmac_f32_e32 v63, v61, v61
	v_fmac_f32_e32 v124, v121, v121
	v_cvt_pk_bf16_f32 v53, v60, v61
	v_add_f32_e32 v60, v63, v124
	ds_bpermute_b32 v61, v187, v60
	v_cvt_pk_bf16_f32 v52, v58, v59
	v_lshl_add_u64 v[58:59], s[26:27], 0, v[136:137]
	v_cvt_pk_bf16_f32 v51, v64, v65
	v_lshl_add_u64 v[58:59], v[196:197], 1, v[58:59]
	global_store_dwordx4 v[58:59], v[50:53], off
	s_waitcnt lgkmcnt(0)
	s_nop 0
	v_add_f32_e32 v50, v60, v61
	ds_bpermute_b32 v51, v189, v50
	v_cvt_pk_bf16_f32 v52, v54, v55
	v_cvt_pk_bf16_f32 v53, v56, v57
	v_cvt_pk_bf16_f32 v54, v122, v123
	v_cvt_pk_bf16_f32 v55, v120, v121
	global_store_dwordx4 v[58:59], v[52:55], off offset:256
	s_and_saveexec_b64 s[14:15], vcc
	s_cbranch_execz .LBB0_541
	s_add_i32 s16, 0, 0x20000
	s_waitcnt lgkmcnt(0)
	v_add_f32_e32 v50, v50, v51
	v_lshl_add_u32 v51, v214, 2, s16
	ds_add_f32 v51, v50 offset:512

.LBB0_562:
	s_add_u32 s40, s6, s0
	ds_read_b128 v[112:115], v211
	ds_read_b128 v[116:119], v211 offset:1024
	ds_read_b128 v[128:131], v211 offset:2048
	ds_read_b128 v[132:135], v211 offset:3072
	s_addc_u32 s41, s7, s1
	s_add_u32 s40, s40, 0x10000100
	s_addc_u32 s41, s41, 0
	s_add_u32 s65, s62, s0
	s_addc_u32 s66, s63, s1
	s_cmpk_eq_i32 s0, 0x700
	s_cselect_b32 s43, s15, s41
	s_cselect_b32 s42, s14, s40
	s_cselect_b32 s41, s60, s66
	s_cselect_b32 s40, s61, s65
	v_lshl_add_u64 v[176:177], v[198:199], 0, s[0:1]
	s_add_i32 m0, s49, 0xc000
	ds_read_b128 v[144:147], v212
	ds_read_b128 v[148:151], v212 offset:1024
	ds_read_b128 v[152:155], v212 offset:2048
	ds_read_b128 v[156:159], v212 offset:3072
	ds_read_b128 v[160:163], v212 offset:4096
	ds_read_b128 v[164:167], v212 offset:5120
	ds_read_b128 v[168:171], v212 offset:6144
	ds_read_b128 v[172:175], v212 offset:7168
	global_load_lds_dwordx4 v[176:177], off
	v_lshl_add_u64 v[176:177], v[200:201], 0, s[0:1]
	s_add_i32 m0, s49, 0xe000
	s_nop 0
	global_load_lds_dwordx4 v[176:177], off
	s_waitcnt lgkmcnt(8)
	s_barrier
	s_waitcnt lgkmcnt(0)
	s_setprio 1
	s_waitcnt lgkmcnt(0)
	v_mfma_f32_16x16x32_bf16 v[140:143], v[112:115], v[144:147], v[140:143]
	v_mfma_f32_16x16x32_bf16 v[136:139], v[128:131], v[144:147], v[136:139]
	v_mfma_f32_16x16x32_bf16 v[108:111], v[112:115], v[152:155], v[108:111]
	v_mfma_f32_16x16x32_bf16 v[104:107], v[128:131], v[152:155], v[104:107]
	v_mfma_f32_16x16x32_bf16 v[92:95], v[112:115], v[160:163], v[92:95]
	v_mfma_f32_16x16x32_bf16 v[88:91], v[128:131], v[160:163], v[88:91]
	v_mfma_f32_16x16x32_bf16 v[76:79], v[112:115], v[168:171], v[76:79]
	v_mfma_f32_16x16x32_bf16 v[72:75], v[128:131], v[168:171], v[72:75]
	v_mfma_f32_16x16x32_bf16 v[140:143], v[116:119], v[148:151], v[140:143]
	v_mfma_f32_16x16x32_bf16 v[136:139], v[132:135], v[148:151], v[136:139]
	v_mfma_f32_16x16x32_bf16 v[108:111], v[116:119], v[156:159], v[108:111]
	v_mfma_f32_16x16x32_bf16 v[104:107], v[132:135], v[156:159], v[104:107]
	v_mfma_f32_16x16x32_bf16 v[92:95], v[116:119], v[164:167], v[92:95]
	v_mfma_f32_16x16x32_bf16 v[88:91], v[132:135], v[164:167], v[88:91]
	v_mfma_f32_16x16x32_bf16 v[76:79], v[116:119], v[172:175], v[76:79]
	v_mfma_f32_16x16x32_bf16 v[72:75], v[132:135], v[172:175], v[72:75]
	s_setprio 0
	s_barrier
	s_add_i32 s65, s45, s3
	v_lshl_add_u64 v[206:207], s[40:41], 0, v[194:195]
	s_mov_b32 m0, s65
	ds_read_b128 v[176:179], v213
	ds_read_b128 v[180:183], v213 offset:1024
	ds_read_b128 v[202:205], v213 offset:2048
	ds_read_b128 v[216:219], v213 offset:3072
	global_load_lds_dwordx4 v[206:207], off
	v_lshl_add_u64 v[220:221], s[40:41], 0, v[190:191]
	s_add_i32 m0, s65, 0x2000
	s_nop 0
	global_load_lds_dwordx4 v[220:221], off
	s_barrier
	s_waitcnt lgkmcnt(0)
	s_setprio 1
	s_waitcnt lgkmcnt(0)
	v_mfma_f32_16x16x32_bf16 v[124:127], v[176:179], v[144:147], v[124:127]
	v_mfma_f32_16x16x32_bf16 v[120:123], v[202:205], v[144:147], v[120:123]
	v_mfma_f32_16x16x32_bf16 v[100:103], v[176:179], v[152:155], v[100:103]
	v_mfma_f32_16x16x32_bf16 v[96:99], v[202:205], v[152:155], v[96:99]
	v_mfma_f32_16x16x32_bf16 v[84:87], v[176:179], v[160:163], v[84:87]
	v_mfma_f32_16x16x32_bf16 v[80:83], v[202:205], v[160:163], v[80:83]
	v_mfma_f32_16x16x32_bf16 v[68:71], v[176:179], v[168:171], v[68:71]
	v_mfma_f32_16x16x32_bf16 v[64:67], v[202:205], v[168:171], v[64:67]
	v_mfma_f32_16x16x32_bf16 v[124:127], v[180:183], v[148:151], v[124:127]
	v_mfma_f32_16x16x32_bf16 v[120:123], v[216:219], v[148:151], v[120:123]
	v_mfma_f32_16x16x32_bf16 v[100:103], v[180:183], v[156:159], v[100:103]
	v_mfma_f32_16x16x32_bf16 v[96:99], v[216:219], v[156:159], v[96:99]
	v_mfma_f32_16x16x32_bf16 v[84:87], v[180:183], v[164:167], v[84:87]
	v_mfma_f32_16x16x32_bf16 v[80:83], v[216:219], v[164:167], v[80:83]
	v_mfma_f32_16x16x32_bf16 v[68:71], v[180:183], v[172:175], v[68:71]
	v_mfma_f32_16x16x32_bf16 v[64:67], v[216:219], v[172:175], v[64:67]
	s_setprio 0
	s_mov_b32 m0, s49
	v_lshl_add_u64 v[222:223], s[42:43], 0, v[196:197]
	s_barrier
	ds_read_b128 v[144:147], v212 offset:16384
	ds_read_b128 v[148:151], v212 offset:17408
	ds_read_b128 v[152:155], v212 offset:18432
	ds_read_b128 v[156:159], v212 offset:19456
	ds_read_b128 v[160:163], v212 offset:20480
	ds_read_b128 v[164:167], v212 offset:21504
	ds_read_b128 v[168:171], v212 offset:22528
	ds_read_b128 v[172:175], v212 offset:23552
	global_load_lds_dwordx4 v[222:223], off
	v_lshl_add_u64 v[224:225], s[42:43], 0, v[192:193]
	s_mov_b32 m0, s50
	s_nop 0
	global_load_lds_dwordx4 v[224:225], off
	s_barrier
	s_waitcnt lgkmcnt(0)
	s_setprio 1
	s_waitcnt lgkmcnt(0)
	v_mfma_f32_16x16x32_bf16 v[60:63], v[112:115], v[144:147], v[60:63]
	v_mfma_f32_16x16x32_bf16 v[56:59], v[128:131], v[144:147], v[56:59]
	v_mfma_f32_16x16x32_bf16 v[44:47], v[112:115], v[152:155], v[44:47]
	v_mfma_f32_16x16x32_bf16 v[40:43], v[128:131], v[152:155], v[40:43]
	v_mfma_f32_16x16x32_bf16 v[28:31], v[112:115], v[160:163], v[28:31]
	v_mfma_f32_16x16x32_bf16 v[24:27], v[128:131], v[160:163], v[24:27]
	v_mfma_f32_16x16x32_bf16 v[12:15], v[112:115], v[168:171], v[12:15]
	v_mfma_f32_16x16x32_bf16 v[8:11], v[128:131], v[168:171], v[8:11]
	v_mfma_f32_16x16x32_bf16 v[60:63], v[116:119], v[148:151], v[60:63]
	v_mfma_f32_16x16x32_bf16 v[56:59], v[132:135], v[148:151], v[56:59]
	v_mfma_f32_16x16x32_bf16 v[44:47], v[116:119], v[156:159], v[44:47]
	v_mfma_f32_16x16x32_bf16 v[40:43], v[132:135], v[156:159], v[40:43]
	v_mfma_f32_16x16x32_bf16 v[28:31], v[116:119], v[164:167], v[28:31]
	v_mfma_f32_16x16x32_bf16 v[24:27], v[132:135], v[164:167], v[24:27]
	v_mfma_f32_16x16x32_bf16 v[12:15], v[116:119], v[172:175], v[12:15]
	v_mfma_f32_16x16x32_bf16 v[8:11], v[132:135], v[172:175], v[8:11]
	s_setprio 0
	s_barrier
	s_add_u32 s66, s40, 0x40000
	s_addc_u32 s67, s41, 0
	s_add_i32 s65, s46, s3
	v_lshl_add_u64 v[112:113], s[66:67], 0, v[194:195]
	s_mov_b32 m0, s65
	s_nop 0
	global_load_lds_dwordx4 v[112:113], off
	v_lshl_add_u64 v[112:113], s[66:67], 0, v[190:191]
	s_add_i32 m0, s65, 0x2000
	s_nop 0
	global_load_lds_dwordx4 v[112:113], off
	s_waitcnt vmcnt(6)
	s_barrier
	s_setprio 1
	v_mfma_f32_16x16x32_bf16 v[52:55], v[176:179], v[144:147], v[52:55]
	v_mfma_f32_16x16x32_bf16 v[48:51], v[202:205], v[144:147], v[48:51]
	v_mfma_f32_16x16x32_bf16 v[36:39], v[176:179], v[152:155], v[36:39]
	v_mfma_f32_16x16x32_bf16 v[32:35], v[202:205], v[152:155], v[32:35]
	v_mfma_f32_16x16x32_bf16 v[20:23], v[176:179], v[160:163], v[20:23]
	v_mfma_f32_16x16x32_bf16 v[16:19], v[202:205], v[160:163], v[16:19]
	v_mfma_f32_16x16x32_bf16 v[4:7], v[176:179], v[168:171], v[4:7]
	v_mfma_f32_16x16x32_bf16 v[0:3], v[202:205], v[168:171], v[0:3]
	v_mfma_f32_16x16x32_bf16 v[52:55], v[180:183], v[148:151], v[52:55]
	v_mfma_f32_16x16x32_bf16 v[48:51], v[216:219], v[148:151], v[48:51]
	v_mfma_f32_16x16x32_bf16 v[36:39], v[180:183], v[156:159], v[36:39]
	v_mfma_f32_16x16x32_bf16 v[32:35], v[216:219], v[156:159], v[32:35]
	v_mfma_f32_16x16x32_bf16 v[20:23], v[180:183], v[164:167], v[20:23]
	v_mfma_f32_16x16x32_bf16 v[16:19], v[216:219], v[164:167], v[16:19]
	v_mfma_f32_16x16x32_bf16 v[4:7], v[180:183], v[172:175], v[4:7]
	v_mfma_f32_16x16x32_bf16 v[0:3], v[216:219], v[172:175], v[0:3]
	s_setprio 0
	v_add_u32_e32 v132, s47, v210
	s_barrier
	ds_read_b128 v[112:115], v132
	ds_read_b128 v[116:119], v132 offset:1024
	ds_read_b128 v[128:131], v132 offset:2048
	ds_read_b128 v[132:135], v132 offset:3072
	s_add_u32 s42, s42, 0x40000
	s_addc_u32 s43, s43, 0
	s_mov_b32 m0, s51
	v_lshl_add_u64 v[176:177], s[42:43], 0, v[196:197]
	ds_read_b128 v[144:147], v212 offset:32768
	ds_read_b128 v[148:151], v212 offset:33792
	ds_read_b128 v[152:155], v212 offset:34816
	ds_read_b128 v[156:159], v212 offset:35840
	ds_read_b128 v[160:163], v212 offset:36864
	ds_read_b128 v[164:167], v212 offset:37888
	ds_read_b128 v[168:171], v212 offset:38912
	ds_read_b128 v[172:175], v212 offset:39936
	global_load_lds_dwordx4 v[176:177], off
	v_lshl_add_u64 v[176:177], s[42:43], 0, v[192:193]
	s_mov_b32 m0, s52
	s_nop 0
	global_load_lds_dwordx4 v[176:177], off
	s_waitcnt lgkmcnt(8)
	s_barrier
	s_waitcnt lgkmcnt(0)
	s_setprio 1
	s_waitcnt lgkmcnt(0)
	v_mfma_f32_16x16x32_bf16 v[140:143], v[112:115], v[144:147], v[140:143]
	v_mfma_f32_16x16x32_bf16 v[136:139], v[128:131], v[144:147], v[136:139]
	v_mfma_f32_16x16x32_bf16 v[108:111], v[112:115], v[152:155], v[108:111]
	v_mfma_f32_16x16x32_bf16 v[104:107], v[128:131], v[152:155], v[104:107]
	v_mfma_f32_16x16x32_bf16 v[92:95], v[112:115], v[160:163], v[92:95]
	v_mfma_f32_16x16x32_bf16 v[88:91], v[128:131], v[160:163], v[88:91]
	v_mfma_f32_16x16x32_bf16 v[76:79], v[112:115], v[168:171], v[76:79]
	v_mfma_f32_16x16x32_bf16 v[72:75], v[128:131], v[168:171], v[72:75]
	v_mfma_f32_16x16x32_bf16 v[140:143], v[116:119], v[148:151], v[140:143]
	v_mfma_f32_16x16x32_bf16 v[136:139], v[132:135], v[148:151], v[136:139]
	v_mfma_f32_16x16x32_bf16 v[108:111], v[116:119], v[156:159], v[108:111]
	v_mfma_f32_16x16x32_bf16 v[104:107], v[132:135], v[156:159], v[104:107]
	v_mfma_f32_16x16x32_bf16 v[92:95], v[116:119], v[164:167], v[92:95]
	v_mfma_f32_16x16x32_bf16 v[88:91], v[132:135], v[164:167], v[88:91]
	v_mfma_f32_16x16x32_bf16 v[76:79], v[116:119], v[172:175], v[76:79]
	v_mfma_f32_16x16x32_bf16 v[72:75], v[132:135], v[172:175], v[72:75]
	s_setprio 0
	s_barrier
	s_add_i32 s42, s47, s3
	v_add_u32_e32 v215, s48, v210
	v_lshl_add_u64 v[206:207], v[206:207], 0, s[20:21]
	s_mov_b32 m0, s42
	ds_read_b128 v[176:179], v215
	ds_read_b128 v[180:183], v215 offset:1024
	ds_read_b128 v[202:205], v215 offset:2048
	ds_read_b128 v[216:219], v215 offset:3072
	global_load_lds_dwordx4 v[206:207], off
	v_lshl_add_u64 v[206:207], v[220:221], 0, s[20:21]
	s_add_i32 m0, s42, 0x2000
	s_nop 0
	global_load_lds_dwordx4 v[206:207], off
	s_barrier
	s_waitcnt lgkmcnt(0)
	s_setprio 1
	s_waitcnt lgkmcnt(0)
	v_mfma_f32_16x16x32_bf16 v[124:127], v[176:179], v[144:147], v[124:127]
	v_mfma_f32_16x16x32_bf16 v[120:123], v[202:205], v[144:147], v[120:123]
	v_mfma_f32_16x16x32_bf16 v[100:103], v[176:179], v[152:155], v[100:103]
	v_mfma_f32_16x16x32_bf16 v[96:99], v[202:205], v[152:155], v[96:99]
	v_mfma_f32_16x16x32_bf16 v[84:87], v[176:179], v[160:163], v[84:87]
	v_mfma_f32_16x16x32_bf16 v[80:83], v[202:205], v[160:163], v[80:83]
	v_mfma_f32_16x16x32_bf16 v[68:71], v[176:179], v[168:171], v[68:71]
	v_mfma_f32_16x16x32_bf16 v[64:67], v[202:205], v[168:171], v[64:67]
	v_mfma_f32_16x16x32_bf16 v[124:127], v[180:183], v[148:151], v[124:127]
	v_mfma_f32_16x16x32_bf16 v[120:123], v[216:219], v[148:151], v[120:123]
	v_mfma_f32_16x16x32_bf16 v[100:103], v[180:183], v[156:159], v[100:103]
	v_mfma_f32_16x16x32_bf16 v[96:99], v[216:219], v[156:159], v[96:99]
	v_mfma_f32_16x16x32_bf16 v[84:87], v[180:183], v[164:167], v[84:87]
	v_mfma_f32_16x16x32_bf16 v[80:83], v[216:219], v[164:167], v[80:83]
	v_mfma_f32_16x16x32_bf16 v[68:71], v[180:183], v[172:175], v[68:71]
	v_mfma_f32_16x16x32_bf16 v[64:67], v[216:219], v[172:175], v[64:67]
	s_setprio 0
	s_mov_b32 m0, s56
	v_lshl_add_u64 v[206:207], v[222:223], 0, s[20:21]
	s_barrier
	ds_read_b128 v[144:147], v212 offset:49152
	ds_read_b128 v[148:151], v212 offset:50176
	ds_read_b128 v[152:155], v212 offset:51200
	ds_read_b128 v[156:159], v212 offset:52224
	ds_read_b128 v[160:163], v212 offset:53248
	ds_read_b128 v[164:167], v212 offset:54272
	ds_read_b128 v[168:171], v212 offset:55296
	ds_read_b128 v[172:175], v212 offset:56320
	global_load_lds_dwordx4 v[206:207], off
	v_lshl_add_u64 v[206:207], v[224:225], 0, s[20:21]
	s_mov_b32 m0, s57
	s_nop 0
	global_load_lds_dwordx4 v[206:207], off
	s_barrier
	s_waitcnt lgkmcnt(0)
	s_setprio 1
	s_waitcnt lgkmcnt(0)
	v_mfma_f32_16x16x32_bf16 v[60:63], v[112:115], v[144:147], v[60:63]
	v_mfma_f32_16x16x32_bf16 v[56:59], v[128:131], v[144:147], v[56:59]
	v_mfma_f32_16x16x32_bf16 v[44:47], v[112:115], v[152:155], v[44:47]
	v_mfma_f32_16x16x32_bf16 v[40:43], v[128:131], v[152:155], v[40:43]
	v_mfma_f32_16x16x32_bf16 v[28:31], v[112:115], v[160:163], v[28:31]
	v_mfma_f32_16x16x32_bf16 v[24:27], v[128:131], v[160:163], v[24:27]
	v_mfma_f32_16x16x32_bf16 v[12:15], v[112:115], v[168:171], v[12:15]
	v_mfma_f32_16x16x32_bf16 v[8:11], v[128:131], v[168:171], v[8:11]
	v_mfma_f32_16x16x32_bf16 v[60:63], v[116:119], v[148:151], v[60:63]
	v_mfma_f32_16x16x32_bf16 v[56:59], v[132:135], v[148:151], v[56:59]
	v_mfma_f32_16x16x32_bf16 v[44:47], v[116:119], v[156:159], v[44:47]
	v_mfma_f32_16x16x32_bf16 v[40:43], v[132:135], v[156:159], v[40:43]
	v_mfma_f32_16x16x32_bf16 v[28:31], v[116:119], v[164:167], v[28:31]
	v_mfma_f32_16x16x32_bf16 v[24:27], v[132:135], v[164:167], v[24:27]
	v_mfma_f32_16x16x32_bf16 v[12:15], v[116:119], v[172:175], v[12:15]
	v_mfma_f32_16x16x32_bf16 v[8:11], v[132:135], v[172:175], v[8:11]
	s_setprio 0
	s_barrier
	s_add_u32 s40, s40, 0x40080
	s_addc_u32 s41, s41, 0
	s_add_i32 s42, s48, s3
	v_lshl_add_u64 v[112:113], s[40:41], 0, v[194:195]
	s_mov_b32 m0, s42
	s_nop 0
	global_load_lds_dwordx4 v[112:113], off
	v_lshl_add_u64 v[112:113], s[40:41], 0, v[190:191]
	s_add_i32 m0, s42, 0x2000
	s_nop 0
	global_load_lds_dwordx4 v[112:113], off
	s_waitcnt vmcnt(6)
	s_barrier
	s_setprio 1
	v_mfma_f32_16x16x32_bf16 v[52:55], v[176:179], v[144:147], v[52:55]
	v_mfma_f32_16x16x32_bf16 v[48:51], v[202:205], v[144:147], v[48:51]
	v_mfma_f32_16x16x32_bf16 v[36:39], v[176:179], v[152:155], v[36:39]
	v_mfma_f32_16x16x32_bf16 v[32:35], v[202:205], v[152:155], v[32:35]
	v_mfma_f32_16x16x32_bf16 v[20:23], v[176:179], v[160:163], v[20:23]
	v_mfma_f32_16x16x32_bf16 v[16:19], v[202:205], v[160:163], v[16:19]
	v_mfma_f32_16x16x32_bf16 v[4:7], v[176:179], v[168:171], v[4:7]
	v_mfma_f32_16x16x32_bf16 v[0:3], v[202:205], v[168:171], v[0:3]
	v_mfma_f32_16x16x32_bf16 v[52:55], v[180:183], v[148:151], v[52:55]
	v_mfma_f32_16x16x32_bf16 v[48:51], v[216:219], v[148:151], v[48:51]
	v_mfma_f32_16x16x32_bf16 v[36:39], v[180:183], v[156:159], v[36:39]
	v_mfma_f32_16x16x32_bf16 v[32:35], v[216:219], v[156:159], v[32:35]
	v_mfma_f32_16x16x32_bf16 v[20:23], v[180:183], v[164:167], v[20:23]
	v_mfma_f32_16x16x32_bf16 v[16:19], v[216:219], v[164:167], v[16:19]
	v_mfma_f32_16x16x32_bf16 v[4:7], v[180:183], v[172:175], v[4:7]
	v_mfma_f32_16x16x32_bf16 v[0:3], v[216:219], v[172:175], v[0:3]
	s_setprio 0
	s_add_i32 s64, s64, 2
	s_add_u32 s0, s0, 0x100
	s_addc_u32 s1, s1, 0
	s_cmp_gt_u32 s64, 13
	s_barrier
	s_cbranch_scc0 .LBB0_562
	v_mov_b32_e32 v112, v208
	v_mov_b32_e32 v118, v209
	s_lshl_b32 s0, s59, 8
	v_add_u32_e32 v215, s54, v112
	v_add_u32_e32 v204, s44, v215
	s_or_b32 s0, s0, s55
	v_lshl_add_u32 v202, v118, 3, s0
	v_ashrrev_i32_e32 v205, 31, v204
	v_ashrrev_i32_e32 v203, 31, v202
	v_lshlrev_b64 v[112:113], 10, v[204:205]
	v_lshl_add_u64 v[112:113], v[112:113], 0, v[202:203]
	v_lshlrev_b64 v[112:113], 1, v[112:113]
	v_lshl_add_u64 v[114:115], s[24:25], 0, v[112:113]
	global_load_dwordx4 v[218:221], v[114:115], off nt
	v_lshl_add_u64 v[116:117], s[26:27], 0, v[112:113]
	global_load_dwordx4 v[222:225], v[116:117], off nt
	v_lshl_add_u32 v217, v215, 2, 0
	v_add_u32_e32 v216, 0x20000, v217
	ds_read_b32 v130, v216
	global_load_dwordx4 v[176:179], v[116:117], off offset:256 nt
	global_load_dwordx4 v[180:183], v[114:115], off offset:256 nt
	v_cmp_eq_u32_e32 vcc, 0, v118
	v_lshl_add_u64 v[118:119], v[112:113], 0, s[8:9]
	v_lshl_add_u64 v[128:129], v[112:113], 0, s[22:23]
	v_lshl_add_u64 v[114:115], s[26:27], 0, v[118:119]
	v_lshl_add_u64 v[112:113], v[112:113], 0, s[28:29]
	v_lshl_add_u64 v[116:117], s[24:25], 0, v[118:119]
	v_lshl_add_u64 v[118:119], s[26:27], 0, v[128:129]
	v_lshl_add_u64 v[128:129], s[24:25], 0, v[128:129]
	global_load_dwordx4 v[168:171], v[114:115], off nt
	global_load_dwordx4 v[160:163], v[114:115], off offset:256 nt
	global_load_dwordx4 v[172:175], v[116:117], off nt
	global_load_dwordx4 v[164:167], v[116:117], off offset:256 nt
	global_load_dwordx4 v[152:155], v[118:119], off nt
	global_load_dwordx4 v[144:147], v[118:119], off offset:256 nt
	global_load_dwordx4 v[156:159], v[128:129], off nt
	global_load_dwordx4 v[148:151], v[128:129], off offset:256 nt
	v_lshl_add_u64 v[132:133], s[26:27], 0, v[112:113]
	v_lshl_add_u64 v[226:227], s[24:25], 0, v[112:113]
	s_waitcnt lgkmcnt(0)
	v_fmamk_f32 v112, v130, 0x3a800000, v214
	v_mul_f32_e32 v113, 0x4b800000, v112
	v_cmp_gt_f32_e64 s[0:1], s58, v112
	v_lshlrev_b64 v[206:207], 11, v[204:205]
	s_waitcnt vmcnt(0)
	v_and_b32_e32 v229, 0xffff0000, v220
	v_cndmask_b32_e64 v112, v112, v113, s[0:1]
	v_rsq_f32_e32 v228, v112
	global_load_dwordx4 v[128:131], v[132:133], off nt
	global_load_dwordx4 v[112:115], v[132:133], off offset:256 nt
	s_nop 0
	global_load_dwordx4 v[132:135], v[226:227], off nt
	global_load_dwordx4 v[116:119], v[226:227], off offset:256 nt
	v_and_b32_e32 v227, 0xffff0000, v222
	v_lshlrev_b32_e32 v230, 16, v224
	v_mul_f32_e32 v226, 0x45800000, v228
	v_cndmask_b32_e64 v232, v228, v226, s[0:1]
	v_mul_f32_e32 v140, v140, v232
	v_mul_f32_e32 v136, v136, v232
	v_mul_f32_e32 v141, v141, v232
	v_mul_f32_e32 v142, v142, v232
	v_mul_f32_e32 v140, 0xbfb8aa3b, v140
	v_mul_f32_e32 v136, 0xbfb8aa3b, v136
	v_mul_f32_e32 v137, v137, v232
	v_mul_f32_e32 v141, 0xbfb8aa3b, v141
	v_mul_f32_e32 v142, 0xbfb8aa3b, v142
	v_exp_f32_e32 v140, v140
	v_exp_f32_e32 v136, v136
	v_mul_f32_e32 v137, 0xbfb8aa3b, v137
	v_exp_f32_e32 v141, v141
	v_exp_f32_e32 v142, v142
	v_exp_f32_e32 v137, v137
	v_mul_f32_e32 v143, v143, v232
	v_mul_f32_e32 v138, v138, v232
	v_mul_f32_e32 v233, 0xbfb8aa3b, v143
	v_add_f32_e32 v140, 1.0, v140
	v_add_f32_e32 v143, 1.0, v136
	v_mul_f32_e32 v139, v139, v232
	v_mul_f32_e32 v138, 0xbfb8aa3b, v138
	v_add_f32_e32 v141, 1.0, v141
	v_add_f32_e32 v234, 1.0, v142
	v_rcp_f32_e32 v136, v140
	v_rcp_f32_e32 v140, v143
	v_lshlrev_b32_e32 v142, 16, v218
	v_and_b32_e32 v143, 0xffff0000, v218
	v_exp_f32_e32 v218, v233
	v_mul_f32_e32 v139, 0xbfb8aa3b, v139
	v_exp_f32_e32 v138, v138
	v_add_f32_e32 v226, 1.0, v137
	v_rcp_f32_e32 v137, v141
	v_exp_f32_e32 v139, v139
	v_mul_f32_e32 v124, v124, v232
	v_mul_f32_e32 v125, v125, v232
	v_mul_f32_e32 v124, 0xbfb8aa3b, v124
	v_mul_f32_e32 v120, v120, v232
	v_mul_f32_e32 v125, 0xbfb8aa3b, v125
	v_mul_f32_e32 v121, v121, v232
	v_rcp_f32_e32 v141, v226
	v_lshlrev_b32_e32 v226, 16, v222
	v_add_f32_e32 v218, 1.0, v218
	v_exp_f32_e32 v124, v124
	v_mul_f32_e32 v120, 0xbfb8aa3b, v120
	v_exp_f32_e32 v125, v125
	v_mul_f32_e32 v121, 0xbfb8aa3b, v121
	v_mul_f32_e32 v126, v126, v232
	v_mul_f32_e32 v127, v127, v232
	v_pk_fma_f32 v[136:137], v[136:137], v[142:143], v[226:227]
	v_rcp_f32_e32 v226, v234
	v_add_f32_e32 v138, 1.0, v138
	v_rcp_f32_e32 v227, v218
	v_add_f32_e32 v139, 1.0, v139
	v_exp_f32_e32 v120, v120
	v_exp_f32_e32 v121, v121
	v_mul_f32_e32 v126, 0xbfb8aa3b, v126
	v_mul_f32_e32 v122, v122, v232
	v_mul_f32_e32 v127, 0xbfb8aa3b, v127
	v_mul_f32_e32 v123, v123, v232
	v_rcp_f32_e32 v138, v138
	v_rcp_f32_e32 v139, v139
	v_exp_f32_e32 v126, v126
	v_mul_f32_e32 v122, 0xbfb8aa3b, v122
	v_exp_f32_e32 v127, v127
	v_mul_f32_e32 v123, 0xbfb8aa3b, v123
	v_exp_f32_e32 v122, v122
	v_exp_f32_e32 v123, v123
	v_lshlrev_b32_e32 v218, 16, v219
	v_and_b32_e32 v219, 0xffff0000, v219
	v_lshlrev_b32_e32 v222, 16, v223
	v_and_b32_e32 v223, 0xffff0000, v223
	v_add_f32_e32 v124, 1.0, v124
	v_add_f32_e32 v125, 1.0, v125
	v_lshlrev_b32_e32 v228, 16, v220
	v_and_b32_e32 v231, 0xffff0000, v224
	v_pk_fma_f32 v[218:219], v[226:227], v[218:219], v[222:223]
	v_lshlrev_b32_e32 v220, 16, v221
	v_and_b32_e32 v221, 0xffff0000, v221
	v_lshlrev_b32_e32 v222, 16, v225
	v_and_b32_e32 v223, 0xffff0000, v225
	v_rcp_f32_e32 v124, v124
	v_add_f32_e32 v120, 1.0, v120
	v_rcp_f32_e32 v125, v125
	v_add_f32_e32 v121, 1.0, v121
	v_pk_fma_f32 v[140:141], v[140:141], v[228:229], v[230:231]
	v_pk_fma_f32 v[220:221], v[138:139], v[220:221], v[222:223]
	v_rcp_f32_e32 v120, v120
	v_rcp_f32_e32 v121, v121
	v_add_f32_e32 v126, 1.0, v126
	v_add_f32_e32 v127, 1.0, v127
	v_pk_mul_f32 v[142:143], v[140:141], v[140:141]
	v_pk_mul_f32 v[138:139], v[220:221], v[220:221]
	v_rcp_f32_e32 v126, v126
	v_add_f32_e32 v122, 1.0, v122
	v_rcp_f32_e32 v127, v127
	v_add_f32_e32 v123, 1.0, v123
	v_pk_fma_f32 v[142:143], v[136:137], v[136:137], v[142:143]
	v_pk_fma_f32 v[222:223], v[218:219], v[218:219], v[138:139]
	v_cvt_pk_bf16_f32 v136, v136, v137
	v_cvt_pk_bf16_f32 v137, v218, v219
	v_cvt_pk_bf16_f32 v138, v140, v141
	v_lshlrev_b32_e32 v140, 16, v180
	v_and_b32_e32 v141, 0xffff0000, v180
	v_lshlrev_b32_e32 v218, 16, v176
	v_and_b32_e32 v219, 0xffff0000, v176
	v_rcp_f32_e32 v122, v122
	v_rcp_f32_e32 v123, v123
	v_pk_fma_f32 v[124:125], v[124:125], v[140:141], v[218:219]
	v_lshlrev_b32_e32 v140, 16, v182
	v_and_b32_e32 v141, 0xffff0000, v182
	v_lshlrev_b32_e32 v218, 16, v178
	v_and_b32_e32 v219, 0xffff0000, v178
	v_pk_fma_f32 v[140:141], v[120:121], v[140:141], v[218:219]
	v_lshlrev_b32_e32 v180, 16, v181
	v_and_b32_e32 v181, 0xffff0000, v181
	v_lshlrev_b32_e32 v176, 16, v177
	v_and_b32_e32 v177, 0xffff0000, v177
	v_add_f32_e32 v142, v142, v143
	v_pk_mul_f32 v[120:121], v[140:141], v[140:141]
	v_pk_fma_f32 v[126:127], v[126:127], v[180:181], v[176:177]
	v_lshlrev_b32_e32 v176, 16, v183
	v_and_b32_e32 v177, 0xffff0000, v183
	v_lshlrev_b32_e32 v178, 16, v179
	v_and_b32_e32 v179, 0xffff0000, v179
	v_add_f32_e32 v142, v222, v142
	v_pk_fma_f32 v[120:121], v[124:125], v[124:125], v[120:121]
	v_pk_fma_f32 v[176:177], v[122:123], v[176:177], v[178:179]
	v_add_f32_e32 v142, v223, v142
	v_pk_mul_f32 v[122:123], v[176:177], v[176:177]
	v_add_f32_e32 v120, v120, v142
	v_pk_fma_f32 v[122:123], v[126:127], v[126:127], v[122:123]
	v_add_f32_e32 v120, v121, v120
	v_add_f32_e32 v120, v122, v120
	v_add_f32_e32 v123, v123, v120
	ds_bpermute_b32 v178, v187, v123
	v_lshl_add_u64 v[120:121], s[18:19], 0, v[206:207]
	v_lshl_add_u64 v[142:143], v[202:203], 1, v[120:121]
	v_cvt_pk_bf16_f32 v139, v220, v221
	v_cvt_pk_bf16_f32 v122, v124, v125
	s_waitcnt lgkmcnt(0)
	v_add_f32_e32 v120, v123, v178
	ds_bpermute_b32 v121, v189, v120
	v_cvt_pk_bf16_f32 v123, v126, v127
	v_cvt_pk_bf16_f32 v124, v140, v141
	v_cvt_pk_bf16_f32 v125, v176, v177
	global_store_dwordx4 v[142:143], v[136:139], off
	global_store_dwordx4 v[142:143], v[122:125], off offset:256
	s_and_saveexec_b64 s[0:1], vcc
	s_cbranch_execz .LBB0_565
	s_waitcnt lgkmcnt(0)
	v_add_f32_e32 v120, v120, v121
	v_add_u32_e32 v121, 0x20400, v217
	ds_add_f32 v121, v120

.LBB0_571:
	s_or_b64 exec, exec, s[0:1]
	s_waitcnt lgkmcnt(0)
	v_lshlrev_b64 v[64:65], 10, v[204:205]
	v_lshl_add_u64 v[64:65], v[64:65], 0, v[202:203]
	v_lshlrev_b64 v[64:65], 1, v[64:65]
	v_lshl_add_u64 v[66:67], v[64:65], 0, s[16:17]
	v_lshl_add_u64 v[68:69], s[24:25], 0, v[66:67]
	v_lshl_add_u64 v[66:67], s[26:27], 0, v[66:67]
	global_load_dwordx4 v[120:123], v[68:69], off nt
	global_load_dwordx4 v[124:127], v[66:67], off nt
	v_add_u32_e32 v118, 0x80, v215
	v_add_u32_e32 v70, s44, v118
	v_ashrrev_i32_e32 v71, 31, v70
	v_lshl_add_u64 v[72:73], v[64:65], 0, s[30:31]
	v_lshl_add_u64 v[74:75], v[64:65], 0, s[34:35]
	ds_read_b32 v119, v216 offset:512
	v_lshlrev_b64 v[116:117], 11, v[70:71]
	v_lshl_add_u64 v[70:71], s[26:27], 0, v[72:73]
	v_lshl_add_u64 v[72:73], s[24:25], 0, v[72:73]
	v_lshl_add_u64 v[76:77], s[26:27], 0, v[74:75]
	v_lshl_add_u64 v[74:75], s[24:25], 0, v[74:75]
	global_load_dwordx4 v[112:115], v[66:67], off offset:256 nt
	global_load_dwordx4 v[128:131], v[68:69], off offset:256 nt
	global_load_dwordx4 v[104:107], v[70:71], off nt
	global_load_dwordx4 v[96:99], v[70:71], off offset:256 nt
	global_load_dwordx4 v[108:111], v[72:73], off nt
	global_load_dwordx4 v[100:103], v[72:73], off offset:256 nt
	global_load_dwordx4 v[88:91], v[76:77], off nt
	global_load_dwordx4 v[80:83], v[76:77], off offset:256 nt
	global_load_dwordx4 v[92:95], v[74:75], off nt
	global_load_dwordx4 v[84:87], v[74:75], off offset:256 nt
	v_lshl_add_u64 v[64:65], v[64:65], 0, s[36:37]
	v_lshl_add_u64 v[78:79], s[26:27], 0, v[64:65]
	v_lshl_add_u64 v[132:133], s[24:25], 0, v[64:65]
	s_waitcnt lgkmcnt(0)
	v_fmamk_f32 v64, v119, 0x3a800000, v214
	v_mul_f32_e32 v65, 0x4b800000, v64
	v_cmp_gt_f32_e64 s[0:1], s58, v64
	s_waitcnt vmcnt(11)
	v_lshlrev_b32_e32 v136, 16, v122
	v_cndmask_b32_e64 v64, v64, v65, s[0:1]
	v_rsq_f32_e32 v119, v64
	global_load_dwordx4 v[72:75], v[78:79], off nt
	global_load_dwordx4 v[64:67], v[78:79], off offset:256 nt
	s_nop 0
	global_load_dwordx4 v[76:79], v[132:133], off nt
	global_load_dwordx4 v[68:71], v[132:133], off offset:256 nt
	s_waitcnt vmcnt(14)
	v_lshlrev_b32_e32 v134, 16, v124
	v_and_b32_e32 v135, 0xffff0000, v124
	v_mul_f32_e32 v132, 0x45800000, v119
	v_cndmask_b32_e64 v119, v119, v132, s[0:1]
	v_mul_f32_e32 v62, v62, v119
	v_mul_f32_e32 v63, v63, v119
	v_mul_f32_e32 v60, v60, v119
	v_mul_f32_e32 v56, v56, v119
	v_mul_f32_e32 v61, v61, v119
	v_mul_f32_e32 v57, v57, v119
	v_mul_f32_e32 v58, v58, v119
	v_mul_f32_e32 v62, 0xbfb8aa3b, v62
	v_mul_f32_e32 v63, 0xbfb8aa3b, v63
	v_mul_f32_e32 v59, v59, v119
	v_mul_f32_e32 v60, 0xbfb8aa3b, v60
	v_mul_f32_e32 v56, 0xbfb8aa3b, v56
	v_mul_f32_e32 v61, 0xbfb8aa3b, v61
	v_mul_f32_e32 v57, 0xbfb8aa3b, v57
	v_mul_f32_e32 v58, 0xbfb8aa3b, v58
	v_exp_f32_e32 v62, v62
	v_exp_f32_e32 v63, v63
	v_mul_f32_e32 v59, 0xbfb8aa3b, v59
	v_exp_f32_e32 v60, v60
	v_exp_f32_e32 v56, v56
	v_exp_f32_e32 v61, v61
	v_exp_f32_e32 v57, v57
	v_exp_f32_e32 v58, v58
	v_exp_f32_e32 v59, v59
	v_mul_f32_e32 v52, v52, v119
	v_mul_f32_e32 v53, v53, v119
	v_mul_f32_e32 v52, 0xbfb8aa3b, v52
	v_mul_f32_e32 v48, v48, v119
	v_mul_f32_e32 v53, 0xbfb8aa3b, v53
	v_mul_f32_e32 v49, v49, v119
	v_add_f32_e32 v62, 1.0, v62
	v_add_f32_e32 v63, 1.0, v63
	v_exp_f32_e32 v52, v52
	v_mul_f32_e32 v48, 0xbfb8aa3b, v48
	v_exp_f32_e32 v53, v53
	v_mul_f32_e32 v49, 0xbfb8aa3b, v49
	v_mul_f32_e32 v54, v54, v119
	v_mul_f32_e32 v55, v55, v119
	v_add_f32_e32 v60, 1.0, v60
	v_add_f32_e32 v132, 1.0, v56
	v_add_f32_e32 v61, 1.0, v61
	v_add_f32_e32 v133, 1.0, v57
	v_add_f32_e32 v58, 1.0, v58
	v_rcp_f32_e32 v62, v62
	v_rcp_f32_e32 v63, v63
	v_add_f32_e32 v59, 1.0, v59
	v_exp_f32_e32 v48, v48
	v_exp_f32_e32 v49, v49
	v_mul_f32_e32 v54, 0xbfb8aa3b, v54
	v_mul_f32_e32 v50, v50, v119
	v_mul_f32_e32 v55, 0xbfb8aa3b, v55
	v_mul_f32_e32 v51, v51, v119
	v_rcp_f32_e32 v56, v60
	v_rcp_f32_e32 v60, v132
	v_rcp_f32_e32 v57, v61
	v_rcp_f32_e32 v61, v133
	v_rcp_f32_e32 v58, v58
	v_rcp_f32_e32 v59, v59
	v_exp_f32_e32 v54, v54
	v_mul_f32_e32 v50, 0xbfb8aa3b, v50
	v_exp_f32_e32 v55, v55
	v_mul_f32_e32 v51, 0xbfb8aa3b, v51
	v_exp_f32_e32 v50, v50
	v_exp_f32_e32 v51, v51
	v_lshlrev_b32_e32 v132, 16, v120
	v_and_b32_e32 v133, 0xffff0000, v120
	v_lshlrev_b32_e32 v120, 16, v121
	v_and_b32_e32 v121, 0xffff0000, v121
	v_lshlrev_b32_e32 v124, 16, v125
	v_and_b32_e32 v125, 0xffff0000, v125
	v_add_f32_e32 v52, 1.0, v52
	v_add_f32_e32 v53, 1.0, v53
	v_and_b32_e32 v137, 0xffff0000, v122
	v_lshlrev_b32_e32 v138, 16, v126
	v_and_b32_e32 v139, 0xffff0000, v126
	v_pk_fma_f32 v[62:63], v[62:63], v[120:121], v[124:125]
	v_lshlrev_b32_e32 v120, 16, v123
	v_and_b32_e32 v121, 0xffff0000, v123
	v_lshlrev_b32_e32 v122, 16, v127
	v_and_b32_e32 v123, 0xffff0000, v127
	v_rcp_f32_e32 v52, v52
	v_add_f32_e32 v48, 1.0, v48
	v_rcp_f32_e32 v53, v53
	v_add_f32_e32 v49, 1.0, v49
	v_pk_fma_f32 v[60:61], v[60:61], v[136:137], v[138:139]
	v_pk_fma_f32 v[120:121], v[58:59], v[120:121], v[122:123]
	v_rcp_f32_e32 v48, v48
	v_rcp_f32_e32 v49, v49
	v_add_f32_e32 v54, 1.0, v54
	v_add_f32_e32 v55, 1.0, v55
	v_pk_fma_f32 v[56:57], v[56:57], v[132:133], v[134:135]
	v_pk_mul_f32 v[132:133], v[60:61], v[60:61]
	v_pk_mul_f32 v[58:59], v[120:121], v[120:121]
	v_rcp_f32_e32 v54, v54
	v_add_f32_e32 v50, 1.0, v50
	v_rcp_f32_e32 v55, v55
	v_add_f32_e32 v51, 1.0, v51
	v_pk_fma_f32 v[132:133], v[56:57], v[56:57], v[132:133]
	v_pk_fma_f32 v[122:123], v[62:63], v[62:63], v[58:59]
	v_cvt_pk_bf16_f32 v56, v56, v57
	v_cvt_pk_bf16_f32 v57, v62, v63
	v_cvt_pk_bf16_f32 v58, v60, v61
	s_waitcnt vmcnt(12)
	v_lshlrev_b32_e32 v60, 16, v128
	v_and_b32_e32 v61, 0xffff0000, v128
	v_lshlrev_b32_e32 v62, 16, v112
	v_and_b32_e32 v63, 0xffff0000, v112
	v_rcp_f32_e32 v50, v50
	v_rcp_f32_e32 v51, v51
	v_pk_fma_f32 v[52:53], v[52:53], v[60:61], v[62:63]
	v_lshlrev_b32_e32 v60, 16, v130
	v_and_b32_e32 v61, 0xffff0000, v130
	v_lshlrev_b32_e32 v62, 16, v114
	v_and_b32_e32 v63, 0xffff0000, v114
	v_pk_fma_f32 v[60:61], v[48:49], v[60:61], v[62:63]
	v_lshlrev_b32_e32 v62, 16, v129
	v_and_b32_e32 v63, 0xffff0000, v129
	v_lshlrev_b32_e32 v112, 16, v113
	v_and_b32_e32 v113, 0xffff0000, v113
	v_pk_fma_f32 v[54:55], v[54:55], v[62:63], v[112:113]
	v_lshlrev_b32_e32 v62, 16, v131
	v_and_b32_e32 v63, 0xffff0000, v131
	v_lshlrev_b32_e32 v112, 16, v115
	v_and_b32_e32 v113, 0xffff0000, v115
	v_pk_fma_f32 v[62:63], v[50:51], v[62:63], v[112:113]
	v_add_f32_e32 v112, v132, v133
	v_pk_mul_f32 v[48:49], v[60:61], v[60:61]
	v_add_f32_e32 v112, v122, v112
	v_pk_fma_f32 v[48:49], v[52:53], v[52:53], v[48:49]
	v_add_f32_e32 v112, v123, v112
	v_pk_mul_f32 v[50:51], v[62:63], v[62:63]
	v_add_f32_e32 v48, v48, v112
	v_pk_fma_f32 v[50:51], v[54:55], v[54:55], v[50:51]
	v_add_f32_e32 v48, v49, v48
	v_add_f32_e32 v48, v50, v48
	v_add_f32_e32 v51, v51, v48
	ds_bpermute_b32 v114, v187, v51
	v_lshl_add_u64 v[48:49], s[18:19], 0, v[116:117]
	v_lshl_add_u64 v[112:113], v[202:203], 1, v[48:49]
	v_cvt_pk_bf16_f32 v59, v120, v121
	v_cvt_pk_bf16_f32 v50, v52, v53
	s_waitcnt lgkmcnt(0)
	v_add_f32_e32 v48, v51, v114
	ds_bpermute_b32 v49, v189, v48
	v_cvt_pk_bf16_f32 v51, v54, v55
	v_cvt_pk_bf16_f32 v52, v60, v61
	v_cvt_pk_bf16_f32 v53, v62, v63
	global_store_dwordx4 v[112:113], v[56:59], off
	global_store_dwordx4 v[112:113], v[50:53], off offset:256
	s_and_saveexec_b64 s[0:1], vcc
	s_cbranch_execz .LBB0_573
	s_waitcnt lgkmcnt(0)
	v_add_f32_e32 v48, v48, v49
	v_lshl_add_u32 v49, v118, 2, 0
	v_add_u32_e32 v49, 0x20400, v49
	ds_add_f32 v49, v48

.LBB0_582:
	s_nop 0
	v_lshl_add_u64 v[32:33], v[22:23], 0, s[10:11]
	v_add_co_u32_e32 v28, vcc, s16, v32
	v_mov_b32_e32 v16, s14
	s_nop 0
	v_addc_co_u32_e32 v29, vcc, 0, v33, vcc
	v_add_co_u32_e32 v64, vcc, s18, v32
	ds_read_b128 v[48:51], v16
	ds_read_b128 v[16:19], v16 offset:16
	v_addc_co_u32_e32 v65, vcc, 0, v33, vcc
	global_load_dwordx4 v[52:55], v[64:65], off offset:-4096 nt
	global_load_dwordx4 v[56:59], v[28:29], off offset:1024 nt
	v_lshl_add_u64 v[24:25], v[20:21], 0, s[12:13]
	v_add_co_u32_e64 v34, s[0:1], s17, v24
	s_waitcnt lgkmcnt(1)
	v_fmamk_f32 v47, v50, 0x3a800000, v46
	v_addc_co_u32_e64 v35, s[0:1], 0, v25, s[0:1]
	v_add_co_u32_e64 v30, s[0:1], s19, v24
	s_waitcnt lgkmcnt(0)
	v_fmamk_f32 v16, v16, 0x3a800000, v46
	v_addc_co_u32_e64 v31, s[0:1], 0, v25, s[0:1]
	v_add_co_u32_e64 v40, s[0:1], s20, v24
	v_fmamk_f32 v17, v17, 0x3a800000, v46
	s_nop 0
	v_addc_co_u32_e64 v41, s[0:1], 0, v25, s[0:1]
	v_add_co_u32_e64 v36, s[0:1], s22, v24
	v_mul_f32_e32 v61, 0x4b800000, v16
	s_nop 0
	v_addc_co_u32_e64 v37, s[0:1], 0, v25, s[0:1]
	v_add_co_u32_e64 v42, s[0:1], s21, v32
	v_cmp_gt_f32_e64 s[4:5], s15, v16
	s_nop 0
	v_addc_co_u32_e64 v43, s[0:1], 0, v33, s[0:1]
	v_add_co_u32_e64 v26, s[0:1], s24, v32
	v_fmamk_f32 v32, v48, 0x3a800000, v46
	s_nop 0
	v_addc_co_u32_e64 v27, s[0:1], 0, v33, s[0:1]
	v_add_co_u32_e64 v44, s[0:1], s23, v24
	v_fmamk_f32 v33, v49, 0x3a800000, v46
	s_nop 0
	v_addc_co_u32_e64 v45, s[0:1], 0, v25, s[0:1]
	v_add_co_u32_e64 v38, s[0:1], s25, v24
	v_fmamk_f32 v48, v51, 0x3a800000, v46
	s_nop 0
	v_addc_co_u32_e64 v39, s[0:1], 0, v25, s[0:1]
	v_mul_f32_e32 v49, 0x4b800000, v32
	v_mul_f32_e32 v50, 0x4b800000, v33
	v_cmp_gt_f32_e32 vcc, s15, v33
	v_mul_f32_e32 v51, 0x4b800000, v47
	v_cmp_gt_f32_e64 s[0:1], s15, v47
	v_mul_f32_e32 v60, 0x4b800000, v48
	v_cmp_gt_f32_e64 s[2:3], s15, v48
	v_cmp_gt_f32_e64 s[8:9], s15, v32
	v_mul_f32_e32 v62, 0x4b800000, v17
	v_cmp_gt_f32_e64 s[6:7], s15, v17
	v_cndmask_b32_e64 v32, v32, v49, s[8:9]
	v_cndmask_b32_e32 v33, v33, v50, vcc
	v_cndmask_b32_e64 v47, v47, v51, s[0:1]
	v_cndmask_b32_e64 v48, v48, v60, s[2:3]
	v_cndmask_b32_e64 v16, v16, v61, s[4:5]
	v_cndmask_b32_e64 v17, v17, v62, s[6:7]
	v_rsq_f32_e32 v32, v32
	v_rsq_f32_e32 v33, v33
	v_rsq_f32_e32 v47, v47
	v_rsq_f32_e32 v48, v48
	v_rsq_f32_e32 v49, v16
	v_rsq_f32_e32 v17, v17
	v_mul_f32_e32 v16, 0x45800000, v32
	v_mul_f32_e32 v50, 0x45800000, v33
	v_mul_f32_e32 v51, 0x45800000, v47
	v_mul_f32_e32 v60, 0x45800000, v48
	v_mul_f32_e32 v61, 0x45800000, v49
	v_mul_f32_e32 v62, 0x45800000, v17
	v_cndmask_b32_e64 v16, v32, v16, s[8:9]
	v_cndmask_b32_e32 v32, v33, v50, vcc
	v_cndmask_b32_e64 v66, v47, v51, s[0:1]
	v_cndmask_b32_e64 v68, v48, v60, s[2:3]
	v_cndmask_b32_e64 v70, v49, v61, s[4:5]
	v_cndmask_b32_e64 v72, v17, v62, s[6:7]
	s_add_i32 s14, s14, 32
	s_add_u32 s12, s12, 0x8000
	s_addc_u32 s13, s13, 0
	s_waitcnt vmcnt(1)
	v_lshlrev_b32_e32 v48, 16, v52
	v_and_b32_e32 v49, 0xffff0000, v52
	v_lshlrev_b32_e32 v50, 16, v53
	v_and_b32_e32 v51, 0xffff0000, v53
	v_lshlrev_b32_e32 v52, 16, v54
	v_and_b32_e32 v53, 0xffff0000, v54
	v_lshlrev_b32_e32 v54, 16, v55
	v_and_b32_e32 v55, 0xffff0000, v55
	s_waitcnt vmcnt(0)
	v_lshlrev_b32_e32 v60, 16, v56
	v_and_b32_e32 v61, 0xffff0000, v56
	v_lshlrev_b32_e32 v56, 16, v57
	v_and_b32_e32 v57, 0xffff0000, v57
	v_lshlrev_b32_e32 v62, 16, v58
	v_and_b32_e32 v63, 0xffff0000, v58
	v_lshlrev_b32_e32 v58, 16, v59
	v_and_b32_e32 v59, 0xffff0000, v59
	v_pk_mul_f32 v[48:49], v[16:17], v[48:49] op_sel_hi:[0,1]
	v_pk_mul_f32 v[50:51], v[16:17], v[50:51] op_sel_hi:[0,1]
	v_pk_mul_f32 v[52:53], v[16:17], v[52:53] op_sel_hi:[0,1]
	v_pk_mul_f32 v[54:55], v[16:17], v[54:55] op_sel_hi:[0,1]
	v_pk_mul_f32 v[60:61], v[16:17], v[60:61] op_sel_hi:[0,1]
	v_pk_mul_f32 v[56:57], v[16:17], v[56:57] op_sel_hi:[0,1]
	v_pk_mul_f32 v[74:75], v[16:17], v[62:63] op_sel_hi:[0,1]
	v_pk_mul_f32 v[16:17], v[16:17], v[58:59] op_sel_hi:[0,1]
	v_pk_mul_f32 v[50:51], v[6:7], v[50:51]
	v_pk_mul_f32 v[48:49], v[4:5], v[48:49]
	v_pk_mul_f32 v[54:55], v[2:3], v[54:55]
	v_pk_mul_f32 v[52:53], v[0:1], v[52:53]
	v_pk_mul_f32 v[58:59], v[14:15], v[56:57]
	v_pk_mul_f32 v[56:57], v[12:13], v[60:61]
	v_pk_mul_f32 v[62:63], v[10:11], v[16:17]
	v_pk_mul_f32 v[60:61], v[8:9], v[74:75]
	global_store_dwordx4 v[24:25], v[48:51], off nt
	global_store_dwordx4 v[24:25], v[52:55], off offset:16 nt
	global_store_dwordx4 v[24:25], v[56:59], off offset:2048 nt
	global_store_dwordx4 v[24:25], v[60:63], off offset:2064 nt
	global_load_dwordx4 v[48:51], v[28:29], off offset:2048 nt
	s_nop 0
	global_load_dwordx4 v[52:55], v[28:29], off offset:3072 nt
	s_add_u32 s10, s10, 0x4000
	s_addc_u32 s11, s11, 0
	s_cmp_lg_u32 s12, 0x20000
	s_waitcnt vmcnt(1)
	v_lshlrev_b32_e32 v16, 16, v48
	v_and_b32_e32 v17, 0xffff0000, v48
	v_lshlrev_b32_e32 v28, 16, v49
	v_and_b32_e32 v29, 0xffff0000, v49
	v_lshlrev_b32_e32 v48, 16, v50
	v_and_b32_e32 v49, 0xffff0000, v50
	v_lshlrev_b32_e32 v50, 16, v51
	v_and_b32_e32 v51, 0xffff0000, v51
	s_waitcnt vmcnt(0)
	v_lshlrev_b32_e32 v56, 16, v52
	v_and_b32_e32 v57, 0xffff0000, v52
	v_lshlrev_b32_e32 v52, 16, v53
	v_and_b32_e32 v53, 0xffff0000, v53
	v_lshlrev_b32_e32 v58, 16, v54
	v_and_b32_e32 v59, 0xffff0000, v54
	v_lshlrev_b32_e32 v54, 16, v55
	v_and_b32_e32 v55, 0xffff0000, v55
	v_pk_mul_f32 v[16:17], v[32:33], v[16:17] op_sel_hi:[0,1]
	v_pk_mul_f32 v[28:29], v[32:33], v[28:29] op_sel_hi:[0,1]
	v_pk_mul_f32 v[60:61], v[32:33], v[48:49] op_sel_hi:[0,1]
	v_pk_mul_f32 v[62:63], v[32:33], v[50:51] op_sel_hi:[0,1]
	v_pk_mul_f32 v[56:57], v[32:33], v[56:57] op_sel_hi:[0,1]
	v_pk_mul_f32 v[74:75], v[32:33], v[52:53] op_sel_hi:[0,1]
	v_pk_mul_f32 v[76:77], v[32:33], v[58:59] op_sel_hi:[0,1]
	v_pk_mul_f32 v[32:33], v[32:33], v[54:55] op_sel_hi:[0,1]
	v_pk_mul_f32 v[50:51], v[6:7], v[28:29]
	v_pk_mul_f32 v[48:49], v[4:5], v[16:17]
	v_pk_mul_f32 v[54:55], v[2:3], v[62:63]
	v_pk_mul_f32 v[52:53], v[0:1], v[60:61]
	v_pk_mul_f32 v[58:59], v[14:15], v[74:75]
	v_pk_mul_f32 v[56:57], v[12:13], v[56:57]
	v_pk_mul_f32 v[62:63], v[10:11], v[32:33]
	v_pk_mul_f32 v[60:61], v[8:9], v[76:77]
	global_store_dwordx4 v[30:31], v[48:51], off offset:-4096 nt
	global_store_dwordx4 v[34:35], v[52:55], off offset:16 nt
	global_store_dwordx4 v[34:35], v[56:59], off offset:2048 nt
	global_store_dwordx4 v[34:35], v[60:63], off offset:2064 nt
	global_load_dwordx4 v[32:35], v[64:65], off nt
	s_nop 0
	global_load_dwordx4 v[48:51], v[64:65], off offset:1024 nt
	s_waitcnt vmcnt(1)
	v_lshlrev_b32_e32 v16, 16, v32
	v_and_b32_e32 v17, 0xffff0000, v32
	v_lshlrev_b32_e32 v28, 16, v33
	v_and_b32_e32 v29, 0xffff0000, v33
	v_lshlrev_b32_e32 v32, 16, v34
	v_and_b32_e32 v33, 0xffff0000, v34
	v_lshlrev_b32_e32 v34, 16, v35
	v_and_b32_e32 v35, 0xffff0000, v35
	s_waitcnt vmcnt(0)
	v_lshlrev_b32_e32 v52, 16, v48
	v_and_b32_e32 v53, 0xffff0000, v48
	v_lshlrev_b32_e32 v48, 16, v49
	v_and_b32_e32 v49, 0xffff0000, v49
	v_lshlrev_b32_e32 v54, 16, v50
	v_and_b32_e32 v55, 0xffff0000, v50
	v_lshlrev_b32_e32 v50, 16, v51
	v_and_b32_e32 v51, 0xffff0000, v51
	v_pk_mul_f32 v[16:17], v[66:67], v[16:17] op_sel_hi:[0,1]
	v_pk_mul_f32 v[28:29], v[66:67], v[28:29] op_sel_hi:[0,1]
	v_pk_mul_f32 v[56:57], v[66:67], v[32:33] op_sel_hi:[0,1]
	v_pk_mul_f32 v[58:59], v[66:67], v[34:35] op_sel_hi:[0,1]
	v_pk_mul_f32 v[52:53], v[66:67], v[52:53] op_sel_hi:[0,1]
	v_pk_mul_f32 v[60:61], v[66:67], v[48:49] op_sel_hi:[0,1]
	v_pk_mul_f32 v[62:63], v[66:67], v[54:55] op_sel_hi:[0,1]
	v_pk_mul_f32 v[66:67], v[66:67], v[50:51] op_sel_hi:[0,1]
	v_pk_mul_f32 v[34:35], v[6:7], v[28:29]
	v_pk_mul_f32 v[32:33], v[4:5], v[16:17]
	v_pk_mul_f32 v[50:51], v[2:3], v[58:59]
	v_pk_mul_f32 v[48:49], v[0:1], v[56:57]
	v_pk_mul_f32 v[54:55], v[14:15], v[60:61]
	v_pk_mul_f32 v[52:53], v[12:13], v[52:53]
	v_pk_mul_f32 v[58:59], v[10:11], v[66:67]
	v_pk_mul_f32 v[56:57], v[8:9], v[62:63]
	global_store_dwordx4 v[30:31], v[32:35], off nt
	global_store_dwordx4 v[30:31], v[48:51], off offset:16 nt
	global_store_dwordx4 v[30:31], v[52:55], off offset:2048 nt
	global_store_dwordx4 v[30:31], v[56:59], off offset:2064 nt
	global_load_dwordx4 v[28:31], v[64:65], off offset:2048 nt
	s_nop 0
	global_load_dwordx4 v[32:35], v[64:65], off offset:3072 nt
	s_waitcnt vmcnt(1)
	v_lshlrev_b32_e32 v16, 16, v28
	v_and_b32_e32 v17, 0xffff0000, v28
	v_lshlrev_b32_e32 v28, 16, v29
	v_and_b32_e32 v29, 0xffff0000, v29
	v_lshlrev_b32_e32 v48, 16, v30
	v_and_b32_e32 v49, 0xffff0000, v30
	v_lshlrev_b32_e32 v30, 16, v31
	v_and_b32_e32 v31, 0xffff0000, v31
	s_waitcnt vmcnt(0)
	v_lshlrev_b32_e32 v50, 16, v32
	v_and_b32_e32 v51, 0xffff0000, v32
	v_lshlrev_b32_e32 v32, 16, v33
	v_and_b32_e32 v33, 0xffff0000, v33
	v_lshlrev_b32_e32 v52, 16, v34
	v_and_b32_e32 v53, 0xffff0000, v34
	v_lshlrev_b32_e32 v34, 16, v35
	v_and_b32_e32 v35, 0xffff0000, v35
	v_pk_mul_f32 v[16:17], v[68:69], v[16:17] op_sel_hi:[0,1]
	v_pk_mul_f32 v[28:29], v[68:69], v[28:29] op_sel_hi:[0,1]
	v_pk_mul_f32 v[48:49], v[68:69], v[48:49] op_sel_hi:[0,1]
	v_pk_mul_f32 v[54:55], v[68:69], v[30:31] op_sel_hi:[0,1]
	v_pk_mul_f32 v[56:57], v[68:69], v[50:51] op_sel_hi:[0,1]
	v_pk_mul_f32 v[50:51], v[68:69], v[32:33] op_sel_hi:[0,1]
	v_pk_mul_f32 v[52:53], v[68:69], v[52:53] op_sel_hi:[0,1]
	v_pk_mul_f32 v[58:59], v[68:69], v[34:35] op_sel_hi:[0,1]
	v_pk_mul_f32 v[30:31], v[6:7], v[28:29]
	v_pk_mul_f32 v[28:29], v[4:5], v[16:17]
	v_pk_mul_f32 v[34:35], v[2:3], v[54:55]
	v_pk_mul_f32 v[32:33], v[0:1], v[48:49]
	v_pk_mul_f32 v[50:51], v[14:15], v[50:51]
	v_pk_mul_f32 v[48:49], v[12:13], v[56:57]
	v_pk_mul_f32 v[54:55], v[10:11], v[58:59]
	v_pk_mul_f32 v[52:53], v[8:9], v[52:53]
	global_store_dwordx4 v[36:37], v[28:31], off offset:-4096 nt
	global_store_dwordx4 v[40:41], v[32:35], off offset:16 nt
	global_store_dwordx4 v[40:41], v[48:51], off offset:2048 nt
	global_store_dwordx4 v[40:41], v[52:55], off offset:2064 nt
	global_load_dwordx4 v[28:31], v[26:27], off offset:-4096 nt
	s_nop 0
	global_load_dwordx4 v[32:35], v[42:43], off offset:1024 nt
	s_waitcnt vmcnt(1)
	v_lshlrev_b32_e32 v16, 16, v28
	v_and_b32_e32 v17, 0xffff0000, v28
	v_lshlrev_b32_e32 v28, 16, v29
	v_and_b32_e32 v29, 0xffff0000, v29
	v_lshlrev_b32_e32 v40, 16, v30
	v_and_b32_e32 v41, 0xffff0000, v30
	v_lshlrev_b32_e32 v30, 16, v31
	v_and_b32_e32 v31, 0xffff0000, v31
	s_waitcnt vmcnt(0)
	v_lshlrev_b32_e32 v48, 16, v32
	v_and_b32_e32 v49, 0xffff0000, v32
	v_lshlrev_b32_e32 v32, 16, v33
	v_and_b32_e32 v33, 0xffff0000, v33
	v_lshlrev_b32_e32 v50, 16, v34
	v_and_b32_e32 v51, 0xffff0000, v34
	v_lshlrev_b32_e32 v34, 16, v35
	v_and_b32_e32 v35, 0xffff0000, v35
	v_pk_mul_f32 v[16:17], v[70:71], v[16:17] op_sel_hi:[0,1]
	v_pk_mul_f32 v[28:29], v[70:71], v[28:29] op_sel_hi:[0,1]
	v_pk_mul_f32 v[40:41], v[70:71], v[40:41] op_sel_hi:[0,1]
	v_pk_mul_f32 v[52:53], v[70:71], v[30:31] op_sel_hi:[0,1]
	v_pk_mul_f32 v[48:49], v[70:71], v[48:49] op_sel_hi:[0,1]
	v_pk_mul_f32 v[54:55], v[70:71], v[32:33] op_sel_hi:[0,1]
	v_pk_mul_f32 v[56:57], v[70:71], v[50:51] op_sel_hi:[0,1]
	v_pk_mul_f32 v[58:59], v[70:71], v[34:35] op_sel_hi:[0,1]
	v_pk_mul_f32 v[30:31], v[6:7], v[28:29]
	v_pk_mul_f32 v[28:29], v[4:5], v[16:17]
	v_pk_mul_f32 v[34:35], v[2:3], v[52:53]
	v_pk_mul_f32 v[32:33], v[0:1], v[40:41]
	v_pk_mul_f32 v[50:51], v[14:15], v[54:55]
	v_pk_mul_f32 v[48:49], v[12:13], v[48:49]
	v_pk_mul_f32 v[54:55], v[10:11], v[58:59]
	v_pk_mul_f32 v[52:53], v[8:9], v[56:57]
	global_store_dwordx4 v[36:37], v[28:31], off nt
	global_store_dwordx4 v[36:37], v[32:35], off offset:16 nt
	global_store_dwordx4 v[36:37], v[48:51], off offset:2048 nt
	global_store_dwordx4 v[36:37], v[52:55], off offset:2064 nt
	global_load_dwordx4 v[28:31], v[42:43], off offset:2048 nt
	s_nop 0
	global_load_dwordx4 v[32:35], v[42:43], off offset:3072 nt
	s_waitcnt vmcnt(1)
	v_lshlrev_b32_e32 v16, 16, v28
	v_and_b32_e32 v17, 0xffff0000, v28
	v_lshlrev_b32_e32 v28, 16, v29
	v_and_b32_e32 v29, 0xffff0000, v29
	v_lshlrev_b32_e32 v36, 16, v30
	v_and_b32_e32 v37, 0xffff0000, v30
	v_lshlrev_b32_e32 v30, 16, v31
	v_and_b32_e32 v31, 0xffff0000, v31
	s_waitcnt vmcnt(0)
	v_lshlrev_b32_e32 v40, 16, v32
	v_and_b32_e32 v41, 0xffff0000, v32
	v_lshlrev_b32_e32 v32, 16, v33
	v_and_b32_e32 v33, 0xffff0000, v33
	v_lshlrev_b32_e32 v42, 16, v34
	v_and_b32_e32 v43, 0xffff0000, v34
	v_lshlrev_b32_e32 v34, 16, v35
	v_and_b32_e32 v35, 0xffff0000, v35
	v_pk_mul_f32 v[16:17], v[72:73], v[16:17] op_sel_hi:[0,1]
	v_pk_mul_f32 v[28:29], v[72:73], v[28:29] op_sel_hi:[0,1]
	v_pk_mul_f32 v[36:37], v[72:73], v[36:37] op_sel_hi:[0,1]
	v_pk_mul_f32 v[48:49], v[72:73], v[30:31] op_sel_hi:[0,1]
	v_pk_mul_f32 v[40:41], v[72:73], v[40:41] op_sel_hi:[0,1]
	v_pk_mul_f32 v[50:51], v[72:73], v[32:33] op_sel_hi:[0,1]
	v_pk_mul_f32 v[52:53], v[72:73], v[42:43] op_sel_hi:[0,1]
	v_pk_mul_f32 v[54:55], v[72:73], v[34:35] op_sel_hi:[0,1]
	v_pk_mul_f32 v[30:31], v[6:7], v[28:29]
	v_pk_mul_f32 v[28:29], v[4:5], v[16:17]
	v_pk_mul_f32 v[34:35], v[2:3], v[48:49]
	v_pk_mul_f32 v[32:33], v[0:1], v[36:37]
	v_pk_mul_f32 v[42:43], v[14:15], v[50:51]
	v_pk_mul_f32 v[40:41], v[12:13], v[40:41]
	v_pk_mul_f32 v[50:51], v[10:11], v[54:55]
	v_pk_mul_f32 v[48:49], v[8:9], v[52:53]
	global_store_dwordx4 v[38:39], v[28:31], off offset:-4096 nt
	global_store_dwordx4 v[44:45], v[32:35], off offset:16 nt
	global_store_dwordx4 v[44:45], v[40:43], off offset:2048 nt
	global_store_dwordx4 v[44:45], v[48:51], off offset:2064 nt
	global_load_dwordx4 v[28:31], v[26:27], off nt
	s_nop 0
	global_load_dwordx4 v[32:35], v[26:27], off offset:1024 nt
	v_fmamk_f32 v16, v18, 0x3a800000, v46
	v_mul_f32_e32 v17, 0x4b800000, v16
	v_cmp_gt_f32_e32 vcc, s15, v16
	s_waitcnt vmcnt(1)
	v_lshlrev_b32_e32 v36, 16, v28
	v_cndmask_b32_e32 v16, v16, v17, vcc
	v_rsq_f32_e32 v16, v16
	v_and_b32_e32 v37, 0xffff0000, v28
	v_lshlrev_b32_e32 v28, 16, v29
	v_and_b32_e32 v29, 0xffff0000, v29
	v_mul_f32_e32 v17, 0x45800000, v16
	v_cndmask_b32_e32 v16, v16, v17, vcc
	v_lshlrev_b32_e32 v40, 16, v30
	v_and_b32_e32 v41, 0xffff0000, v30
	v_lshlrev_b32_e32 v30, 16, v31
	v_and_b32_e32 v31, 0xffff0000, v31
	s_waitcnt vmcnt(0)
	v_lshlrev_b32_e32 v42, 16, v32
	v_and_b32_e32 v43, 0xffff0000, v32
	v_lshlrev_b32_e32 v32, 16, v33
	v_and_b32_e32 v33, 0xffff0000, v33
	v_lshlrev_b32_e32 v44, 16, v34
	v_and_b32_e32 v45, 0xffff0000, v34
	v_lshlrev_b32_e32 v34, 16, v35
	v_and_b32_e32 v35, 0xffff0000, v35
	v_pk_mul_f32 v[36:37], v[16:17], v[36:37] op_sel_hi:[0,1]
	v_pk_mul_f32 v[28:29], v[16:17], v[28:29] op_sel_hi:[0,1]
	v_pk_mul_f32 v[40:41], v[16:17], v[40:41] op_sel_hi:[0,1]
	v_pk_mul_f32 v[48:49], v[16:17], v[30:31] op_sel_hi:[0,1]
	v_pk_mul_f32 v[50:51], v[16:17], v[42:43] op_sel_hi:[0,1]
	v_pk_mul_f32 v[42:43], v[16:17], v[32:33] op_sel_hi:[0,1]
	v_pk_mul_f32 v[44:45], v[16:17], v[44:45] op_sel_hi:[0,1]
	v_pk_mul_f32 v[16:17], v[16:17], v[34:35] op_sel_hi:[0,1]
	v_pk_mul_f32 v[30:31], v[6:7], v[28:29]
	v_pk_mul_f32 v[28:29], v[4:5], v[36:37]
	v_pk_mul_f32 v[34:35], v[2:3], v[48:49]
	v_pk_mul_f32 v[32:33], v[0:1], v[40:41]
	v_pk_mul_f32 v[42:43], v[14:15], v[42:43]
	v_pk_mul_f32 v[40:41], v[12:13], v[50:51]
	v_pk_mul_f32 v[50:51], v[10:11], v[16:17]
	v_pk_mul_f32 v[48:49], v[8:9], v[44:45]
	global_store_dwordx4 v[38:39], v[28:31], off nt
	global_store_dwordx4 v[38:39], v[32:35], off offset:16 nt
	global_store_dwordx4 v[38:39], v[40:43], off offset:2048 nt
	global_store_dwordx4 v[38:39], v[48:51], off offset:2064 nt
	global_load_dwordx4 v[28:31], v[26:27], off offset:2048 nt
	s_nop 0
	global_load_dwordx4 v[32:35], v[26:27], off offset:3072 nt
	v_add_co_u32_e32 v36, vcc, s26, v24
	v_fmamk_f32 v16, v19, 0x3a800000, v46
	s_nop 0
	v_addc_co_u32_e32 v37, vcc, 0, v25, vcc
	v_mul_f32_e32 v17, 0x4b800000, v16
	v_cmp_gt_f32_e32 vcc, s15, v16
	s_waitcnt vmcnt(1)
	v_lshlrev_b32_e32 v18, 16, v28
	v_cndmask_b32_e32 v16, v16, v17, vcc
	v_rsq_f32_e32 v16, v16
	v_and_b32_e32 v19, 0xffff0000, v28
	v_lshlrev_b32_e32 v24, 16, v29
	v_and_b32_e32 v25, 0xffff0000, v29
	v_mul_f32_e32 v17, 0x45800000, v16
	v_cndmask_b32_e32 v16, v16, v17, vcc
	v_lshlrev_b32_e32 v26, 16, v30
	v_and_b32_e32 v27, 0xffff0000, v30
	v_lshlrev_b32_e32 v28, 16, v31
	v_and_b32_e32 v29, 0xffff0000, v31
	s_waitcnt vmcnt(0)
	v_lshlrev_b32_e32 v30, 16, v32
	v_and_b32_e32 v31, 0xffff0000, v32
	v_lshlrev_b32_e32 v32, 16, v33
	v_and_b32_e32 v33, 0xffff0000, v33
	v_lshlrev_b32_e32 v38, 16, v34
	v_and_b32_e32 v39, 0xffff0000, v34
	v_lshlrev_b32_e32 v34, 16, v35
	v_and_b32_e32 v35, 0xffff0000, v35
	v_pk_mul_f32 v[40:41], v[16:17], v[18:19] op_sel_hi:[0,1]
	v_pk_mul_f32 v[18:19], v[16:17], v[24:25] op_sel_hi:[0,1]
	v_pk_mul_f32 v[24:25], v[16:17], v[26:27] op_sel_hi:[0,1]
	v_pk_mul_f32 v[26:27], v[16:17], v[28:29] op_sel_hi:[0,1]
	v_pk_mul_f32 v[28:29], v[16:17], v[30:31] op_sel_hi:[0,1]
	v_pk_mul_f32 v[30:31], v[16:17], v[32:33] op_sel_hi:[0,1]
	v_pk_mul_f32 v[32:33], v[16:17], v[38:39] op_sel_hi:[0,1]
	v_pk_mul_f32 v[34:35], v[16:17], v[34:35] op_sel_hi:[0,1]
	v_pk_mul_f32 v[18:19], v[6:7], v[18:19]
	v_pk_mul_f32 v[16:17], v[4:5], v[40:41]
	v_pk_mul_f32 v[26:27], v[2:3], v[26:27]
	v_pk_mul_f32 v[24:25], v[0:1], v[24:25]
	v_pk_mul_f32 v[30:31], v[14:15], v[30:31]
	v_pk_mul_f32 v[28:29], v[12:13], v[28:29]
	v_pk_mul_f32 v[34:35], v[10:11], v[34:35]
	v_pk_mul_f32 v[32:33], v[8:9], v[32:33]
	global_store_dwordx4 v[36:37], v[16:19], off nt
	global_store_dwordx4 v[36:37], v[24:27], off offset:16 nt
	global_store_dwordx4 v[36:37], v[28:31], off offset:2048 nt
	global_store_dwordx4 v[36:37], v[32:35], off offset:2064 nt
	s_cbranch_scc1 .LBB0_582
	s_endpgm
